# latent scan: y reduction as a 16-lane transpose-reduce once per chunk (spread over the next chunk's steps) + context scan y butterfly
# speedup vs baseline: 1.0440x; 1.0078x over previous
.LBB0_961:
	s_waitcnt vmcnt(0) lgkmcnt(0)
	v_readlane_b32 s0, v242, 42
	v_readlane_b32 s1, v242, 43
	v_readlane_b32 s4, v242, 3
	v_readlane_b32 s5, v242, 4
	s_lshr_b32 s6, s24, 2
	s_and_b32 s7, s24, 3
	s_cmp_gt_u32 s6, 11
	s_cselect_b32 s8, 1, 0
	s_mul_i32 s9, s8, 12
	s_sub_i32 s9, s6, s9
	s_sub_u32 s0, s0, 0x118
	s_subb_u32 s1, s1, 0
	s_load_dwordx2 s[2:3], s[0:1], 0x30
	s_lshr_b32 s10, s9, 1
	s_and_b32 s11, s9, 1
	s_lshl_b32 s29, s8, 1
	s_add_i32 s29, s29, 0
	s_lshl_b32 s29, s29, 1
	s_add_i32 s29, s29, s11
	s_mul_i32 s29, s29, 6
	s_add_i32 s29, s29, s10
	s_lshl_b32 s29, s29, 14
	v_and_b32_e32 v20, 15, v137
	v_lshrrev_b32_e32 v21, 4, v137
	v_lshlrev_b32_e32 v22, 4, v137
	s_lshl_b32 s38, s7, 12
	v_add_u32_e32 v22, s38, v22
	s_waitcnt lgkmcnt(0)
	s_add_u32 s2, s2, s29
	s_addc_u32 s3, s3, 0
	global_load_dwordx4 v[0:3], v22, s[2:3]
	s_mul_i32 s38, s11, 0xf00000
	s_mul_i32 s39, s11, 0x780000
	s_add_u32 s29, s38, 0x9278100
	s_add_u32 s12, s4, s29
	s_addc_u32 s13, s5, 0
	s_add_u32 s29, s39, 0xb078100
	s_add_u32 s14, s4, s29
	s_addc_u32 s15, s5, 0
	s_add_u32 s29, s39, 0xbf78100
	s_add_u32 s18, s4, s29
	s_addc_u32 s19, s5, 0
	s_add_u32 s29, s39, 0xddc8100
	s_add_u32 s22, s4, s29
	s_addc_u32 s23, s5, 0
	s_add_u32 s16, s4, 0xce78100
	s_addc_u32 s17, s5, 0
	s_add_u32 s20, s4, 0x5b78100
	s_addc_u32 s21, s5, 0
	s_lshl_b32 s38, s11, 1
	s_sub_i32 s38, 1, s38
	s_mul_i32 s25, s38, 24576
	s_mul_i32 s26, s38, 12288
	s_mul_i32 s27, s38, 0x16000
	s_lshl_b32 s39, s8, 10
	s_addk_i32 s39, 0x2000
	s_mul_i32 s44, s11, 1023
	s_add_i32 s39, s39, s44
	v_mul_i32_i24_e32 v23, s38, v21
	v_mul_i32_i24_e32 v24, s38, v20
	v_add_u32_e32 v23, s39, v23
	v_add_u32_e32 v24, s39, v24
	s_lshl_b32 s38, s10, 8
	s_lshl_b32 s39, s10, 7
	s_movk_i32 s44, 0x600
	v_lshlrev_b32_e32 v25, 4, v20
	v_mul_lo_u32 v174, v23, s44
	v_add3_u32 v174, v174, s38, v25
	s_movk_i32 s44, 0x300
	v_lshlrev_b32_e32 v26, 3, v20
	v_mul_lo_u32 v175, v23, s44
	v_add3_u32 v175, v175, s39, v26
	v_mul_lo_u32 v145, v24, s44
	s_lshl_b32 s44, s7, 5
	s_add_i32 s44, s44, s39
	v_lshlrev_b32_e32 v27, 1, v21
	v_add3_u32 v145, v145, s44, v27
	s_movk_i32 s44, 0x1600
	v_mul_lo_u32 v180, v23, s44
	v_lshlrev_b32_e32 v28, 2, v20
	s_lshl_b32 s44, s7, 6
	s_add_i32 s44, s44, s38
	s_addk_i32 s44, 0xc00
	v_add3_u32 v181, v180, s44, v28
	v_add3_u32 v180, v180, s38, v25
	v_mov_b32_e32 v88, v25
	v_lshlrev_b32_e32 v90, 4, v21
	v_mul_u32_u24_e32 v91, 0x600, v21
	v_add_u32_e32 v91, v91, v25
	v_and_b32_e32 v29, 1, v20
	v_and_b32_e32 v30, 2, v20
	v_cmp_ne_u32_e64 s[30:31], 0, v29
	v_cmp_ne_u32_e64 s[34:35], 0, v30
	v_and_b32_e32 v29, 3, v20
	v_cmp_eq_u32_e64 s[36:37], 3, v29
	s_mov_b32 s28, 0
	s_setprio 3
	global_load_dwordx4 v[104:107], v174, s[12:13]
	global_load_dwordx2 v[146:147], v175, s[14:15]
	global_load_dwordx2 v[148:149], v175, s[16:17]
	global_load_dwordx2 v[150:151], v175, s[18:19]
	global_load_dwordx4 v[108:111], v180, s[20:21]
	global_load_dword v170, v181, s[20:21]
	v_add_u32_e32 v174, s25, v174
	v_add_u32_e32 v175, s26, v175
	v_add_u32_e32 v180, s27, v180
	v_add_u32_e32 v181, s27, v181
	global_load_dwordx4 v[112:115], v174, s[12:13]
	global_load_dwordx2 v[152:153], v175, s[14:15]
	global_load_dwordx2 v[154:155], v175, s[16:17]
	global_load_dwordx2 v[156:157], v175, s[18:19]
	global_load_dwordx4 v[116:119], v180, s[20:21]
	global_load_dword v171, v181, s[20:21]
	v_add_u32_e32 v174, s25, v174
	v_add_u32_e32 v175, s26, v175
	v_add_u32_e32 v180, s27, v180
	v_add_u32_e32 v181, s27, v181
	global_load_dwordx4 v[120:123], v174, s[12:13]
	global_load_dwordx2 v[158:159], v175, s[14:15]
	global_load_dwordx2 v[160:161], v175, s[16:17]
	global_load_dwordx2 v[162:163], v175, s[18:19]
	global_load_dwordx4 v[124:127], v180, s[20:21]
	global_load_dword v172, v181, s[20:21]
	v_add_u32_e32 v174, s25, v174
	v_add_u32_e32 v175, s26, v175
	v_add_u32_e32 v180, s27, v180
	v_add_u32_e32 v181, s27, v181
	global_load_dwordx4 v[128:131], v174, s[12:13]
	global_load_dwordx2 v[164:165], v175, s[14:15]
	global_load_dwordx2 v[166:167], v175, s[16:17]
	global_load_dwordx2 v[168:169], v175, s[18:19]
	global_load_dwordx4 v[132:135], v180, s[20:21]
	global_load_dword v173, v181, s[20:21]
	v_add_u32_e32 v174, s25, v174
	v_add_u32_e32 v175, s26, v175
	v_add_u32_e32 v180, s27, v180
	v_add_u32_e32 v181, s27, v181
	s_waitcnt vmcnt(18)
	ds_write_b128 v91, v[104:107] offset:0
	ds_write_b128 v91, v[108:111] offset:1024
	ds_write_b32 v91, v170 offset:1280
	v_lshlrev_b32_e32 v176, 16, v146
	v_and_b32_e32 v177, 0xffff0000, v146
	v_lshlrev_b32_e32 v178, 16, v147
	v_and_b32_e32 v179, 0xffff0000, v147
	ds_write_b128 v91, v[176:179] offset:256
	v_lshlrev_b32_e32 v176, 16, v148
	v_and_b32_e32 v177, 0xffff0000, v148
	v_lshlrev_b32_e32 v178, 16, v149
	v_and_b32_e32 v179, 0xffff0000, v149
	ds_write_b128 v91, v[176:179] offset:512
	v_lshlrev_b32_e32 v176, 16, v150
	v_and_b32_e32 v177, 0xffff0000, v150
	v_lshlrev_b32_e32 v178, 16, v151
	v_and_b32_e32 v179, 0xffff0000, v151
	ds_write_b128 v91, v[176:179] offset:768
	s_waitcnt lgkmcnt(0)
	s_barrier
	ds_read_b128 v[28:31], v88 offset:512
	ds_read_b128 v[24:27], v88 offset:256
	ds_read_b128 v[20:23], v88 offset:0
	ds_read_b128 v[32:35], v88 offset:768
	ds_read_b128 v[36:39], v88 offset:1024
	ds_read2st64_b32 v[16:17], v90 offset0:5 offset1:11
	ds_read_b128 v[48:51], v88 offset:2048
	ds_read_b128 v[44:47], v88 offset:1792
	ds_read_b128 v[40:43], v88 offset:1536
	ds_read_b128 v[52:55], v88 offset:2304
	ds_read_b128 v[56:59], v88 offset:2560
.Lls0_loop:
	s_waitcnt lgkmcnt(5)
	v_pk_mul_f32 v[4:5], v[0:1], v[28:29] neg_lo:[0,1] neg_hi:[0,1]
	ds_read_b128 v[68:71], v88 offset:3584
	v_pk_fma_f32 v[4:5], v[2:3], v[30:31], v[4:5] neg_lo:[0,1,0] neg_hi:[0,1,0]
	ds_read_b128 v[64:67], v88 offset:3328
	v_pk_mul_f32 v[8:9], v[24:25], v[16:17] op_sel_hi:[1,0]
	v_add_f32_e32 v4, v4, v5
	ds_read_b128 v[60:63], v88 offset:3072
	v_pk_mul_f32 v[10:11], v[26:27], v[16:17] op_sel_hi:[1,0]
	v_add_f32_dpp v4, v4, v4 quad_perm:[1,0,3,2] row_mask:0xf bank_mask:0xf bound_ctrl:1
	ds_read_b128 v[72:75], v88 offset:3840
	v_pk_fma_f32 v[8:9], v[0:1], v[20:21], v[8:9]
	v_add_f32_dpp v4, v4, v4 quad_perm:[2,3,0,1] row_mask:0xf bank_mask:0xf bound_ctrl:1
	v_pk_fma_f32 v[10:11], v[2:3], v[22:23], v[10:11]
	s_nop 0
	v_add_f32_dpp v4, v4, v4 row_ror:4 row_mask:0xf bank_mask:0xf bound_ctrl:1
	ds_read_b128 v[76:79], v88 offset:4096
	s_nop 0
	v_add_f32_dpp v4, v4, v4 row_ror:8 row_mask:0xf bank_mask:0xf bound_ctrl:1
	v_pk_fma_f32 v[0:1], v[4:5], v[32:33], v[8:9] op_sel_hi:[0,1,1]
	v_pk_fma_f32 v[2:3], v[4:5], v[34:35], v[10:11] op_sel_hi:[0,1,1]
	v_pk_mul_f32 v[6:7], v[0:1], v[36:37]
	v_pk_fma_f32 v[6:7], v[2:3], v[38:39], v[6:7]
	v_add_f32_e32 v182, v6, v7
	ds_read2st64_b32 v[18:19], v90 offset0:17 offset1:23
	s_cmp_lt_u32 s28, 15
	s_cbranch_scc0 .Lls0_skip0
	global_load_dwordx4 v[104:107], v174, s[12:13]
	global_load_dwordx2 v[146:147], v175, s[14:15]
	global_load_dwordx2 v[148:149], v175, s[16:17]
	global_load_dwordx2 v[150:151], v175, s[18:19]
	global_load_dwordx4 v[108:111], v180, s[20:21]
	global_load_dword v170, v181, s[20:21]
	v_add_u32_e32 v174, s25, v174
	v_add_u32_e32 v175, s26, v175
	v_add_u32_e32 v180, s27, v180
	v_add_u32_e32 v181, s27, v181
.Lls0_back0:
	v_add_f32_dpp v198, v198, v198 row_ror:8 row_mask:0xf bank_mask:0x3 bound_ctrl:1
	v_add_f32_dpp v198, v206, v206 row_ror:8 row_mask:0xf bank_mask:0xc bound_ctrl:1
	v_add_f32_dpp v199, v199, v199 row_ror:8 row_mask:0xf bank_mask:0x3 bound_ctrl:1
	v_add_f32_dpp v199, v207, v207 row_ror:8 row_mask:0xf bank_mask:0xc bound_ctrl:1
	s_waitcnt lgkmcnt(6)
	v_pk_mul_f32 v[4:5], v[0:1], v[48:49] neg_lo:[0,1] neg_hi:[0,1]
	ds_read_b128 v[92:95], v88 offset:5120
	v_pk_fma_f32 v[4:5], v[2:3], v[50:51], v[4:5] neg_lo:[0,1,0] neg_hi:[0,1,0]
	ds_read_b128 v[84:87], v88 offset:4864
	v_pk_mul_f32 v[8:9], v[44:45], v[16:17] op_sel:[0,1] op_sel_hi:[1,1]
	v_add_f32_e32 v4, v4, v5
	ds_read_b128 v[80:83], v88 offset:4608
	v_pk_mul_f32 v[10:11], v[46:47], v[16:17] op_sel:[0,1] op_sel_hi:[1,1]
	v_add_f32_dpp v4, v4, v4 quad_perm:[1,0,3,2] row_mask:0xf bank_mask:0xf bound_ctrl:1
	ds_read_b128 v[96:99], v88 offset:5376
	v_pk_fma_f32 v[8:9], v[0:1], v[40:41], v[8:9]
	v_add_f32_dpp v4, v4, v4 quad_perm:[2,3,0,1] row_mask:0xf bank_mask:0xf bound_ctrl:1
	v_pk_fma_f32 v[10:11], v[2:3], v[42:43], v[10:11]
	s_nop 0
	v_add_f32_dpp v4, v4, v4 row_ror:4 row_mask:0xf bank_mask:0xf bound_ctrl:1
	ds_read_b128 v[100:103], v88 offset:5632
	s_nop 0
	v_add_f32_dpp v4, v4, v4 row_ror:8 row_mask:0xf bank_mask:0xf bound_ctrl:1
	v_pk_fma_f32 v[0:1], v[4:5], v[52:53], v[8:9] op_sel_hi:[0,1,1]
	v_pk_fma_f32 v[2:3], v[4:5], v[54:55], v[10:11] op_sel_hi:[0,1,1]
	v_pk_mul_f32 v[6:7], v[0:1], v[56:57]
	v_pk_fma_f32 v[6:7], v[2:3], v[58:59], v[6:7]
	v_add_f32_e32 v183, v6, v7
	v_add_f32_dpp v200, v200, v200 row_ror:8 row_mask:0xf bank_mask:0x3 bound_ctrl:1
	v_add_f32_dpp v200, v208, v208 row_ror:8 row_mask:0xf bank_mask:0xc bound_ctrl:1
	v_add_f32_dpp v201, v201, v201 row_ror:8 row_mask:0xf bank_mask:0x3 bound_ctrl:1
	v_add_f32_dpp v201, v209, v209 row_ror:8 row_mask:0xf bank_mask:0xc bound_ctrl:1
	s_waitcnt lgkmcnt(5)
	v_pk_mul_f32 v[4:5], v[0:1], v[68:69] neg_lo:[0,1] neg_hi:[0,1]
	ds_read_b128 v[28:31], v88 offset:6656
	v_pk_fma_f32 v[4:5], v[2:3], v[70:71], v[4:5] neg_lo:[0,1,0] neg_hi:[0,1,0]
	ds_read_b128 v[24:27], v88 offset:6400
	v_pk_mul_f32 v[8:9], v[64:65], v[18:19] op_sel_hi:[1,0]
	v_add_f32_e32 v4, v4, v5
	ds_read_b128 v[20:23], v88 offset:6144
	v_pk_mul_f32 v[10:11], v[66:67], v[18:19] op_sel_hi:[1,0]
	v_add_f32_dpp v4, v4, v4 quad_perm:[1,0,3,2] row_mask:0xf bank_mask:0xf bound_ctrl:1
	ds_read_b128 v[32:35], v88 offset:6912
	v_pk_fma_f32 v[8:9], v[0:1], v[60:61], v[8:9]
	v_add_f32_dpp v4, v4, v4 quad_perm:[2,3,0,1] row_mask:0xf bank_mask:0xf bound_ctrl:1
	v_pk_fma_f32 v[10:11], v[2:3], v[62:63], v[10:11]
	s_nop 0
	v_add_f32_dpp v4, v4, v4 row_ror:4 row_mask:0xf bank_mask:0xf bound_ctrl:1
	ds_read_b128 v[36:39], v88 offset:7168
	s_nop 0
	v_add_f32_dpp v4, v4, v4 row_ror:8 row_mask:0xf bank_mask:0xf bound_ctrl:1
	v_pk_fma_f32 v[0:1], v[4:5], v[72:73], v[8:9] op_sel_hi:[0,1,1]
	v_pk_fma_f32 v[2:3], v[4:5], v[74:75], v[10:11] op_sel_hi:[0,1,1]
	v_pk_mul_f32 v[6:7], v[0:1], v[76:77]
	v_pk_fma_f32 v[6:7], v[2:3], v[78:79], v[6:7]
	v_add_f32_e32 v184, v6, v7
	ds_read2st64_b32 v[16:17], v90 offset0:29 offset1:35
	v_add_f32_dpp v202, v202, v202 row_ror:8 row_mask:0xf bank_mask:0x3 bound_ctrl:1
	v_add_f32_dpp v202, v210, v210 row_ror:8 row_mask:0xf bank_mask:0xc bound_ctrl:1
	v_add_f32_dpp v203, v203, v203 row_ror:8 row_mask:0xf bank_mask:0x3 bound_ctrl:1
	v_add_f32_dpp v203, v211, v211 row_ror:8 row_mask:0xf bank_mask:0xc bound_ctrl:1
	s_waitcnt lgkmcnt(6)
	v_pk_mul_f32 v[4:5], v[0:1], v[92:93] neg_lo:[0,1] neg_hi:[0,1]
	ds_read_b128 v[48:51], v88 offset:8192
	v_pk_fma_f32 v[4:5], v[2:3], v[94:95], v[4:5] neg_lo:[0,1,0] neg_hi:[0,1,0]
	ds_read_b128 v[44:47], v88 offset:7936
	v_pk_mul_f32 v[8:9], v[84:85], v[18:19] op_sel:[0,1] op_sel_hi:[1,1]
	v_add_f32_e32 v4, v4, v5
	ds_read_b128 v[40:43], v88 offset:7680
	v_pk_mul_f32 v[10:11], v[86:87], v[18:19] op_sel:[0,1] op_sel_hi:[1,1]
	v_add_f32_dpp v4, v4, v4 quad_perm:[1,0,3,2] row_mask:0xf bank_mask:0xf bound_ctrl:1
	ds_read_b128 v[52:55], v88 offset:8448
	v_pk_fma_f32 v[8:9], v[0:1], v[80:81], v[8:9]
	v_add_f32_dpp v4, v4, v4 quad_perm:[2,3,0,1] row_mask:0xf bank_mask:0xf bound_ctrl:1
	v_pk_fma_f32 v[10:11], v[2:3], v[82:83], v[10:11]
	s_nop 0
	v_add_f32_dpp v4, v4, v4 row_ror:4 row_mask:0xf bank_mask:0xf bound_ctrl:1
	ds_read_b128 v[56:59], v88 offset:8704
	s_nop 0
	v_add_f32_dpp v4, v4, v4 row_ror:8 row_mask:0xf bank_mask:0xf bound_ctrl:1
	v_pk_fma_f32 v[0:1], v[4:5], v[96:97], v[8:9] op_sel_hi:[0,1,1]
	v_pk_fma_f32 v[2:3], v[4:5], v[98:99], v[10:11] op_sel_hi:[0,1,1]
	v_pk_mul_f32 v[6:7], v[0:1], v[100:101]
	v_pk_fma_f32 v[6:7], v[2:3], v[102:103], v[6:7]
	v_add_f32_e32 v185, v6, v7
	v_add_f32_dpp v204, v204, v204 row_ror:8 row_mask:0xf bank_mask:0x3 bound_ctrl:1
	v_add_f32_dpp v204, v212, v212 row_ror:8 row_mask:0xf bank_mask:0xc bound_ctrl:1
	v_add_f32_dpp v205, v205, v205 row_ror:8 row_mask:0xf bank_mask:0x3 bound_ctrl:1
	v_add_f32_dpp v205, v213, v213 row_ror:8 row_mask:0xf bank_mask:0xc bound_ctrl:1
	s_waitcnt lgkmcnt(5)
	v_pk_mul_f32 v[4:5], v[0:1], v[28:29] neg_lo:[0,1] neg_hi:[0,1]
	ds_read_b128 v[68:71], v88 offset:9728
	v_pk_fma_f32 v[4:5], v[2:3], v[30:31], v[4:5] neg_lo:[0,1,0] neg_hi:[0,1,0]
	ds_read_b128 v[64:67], v88 offset:9472
	v_pk_mul_f32 v[8:9], v[24:25], v[16:17] op_sel_hi:[1,0]
	v_add_f32_e32 v4, v4, v5
	ds_read_b128 v[60:63], v88 offset:9216
	v_pk_mul_f32 v[10:11], v[26:27], v[16:17] op_sel_hi:[1,0]
	v_add_f32_dpp v4, v4, v4 quad_perm:[1,0,3,2] row_mask:0xf bank_mask:0xf bound_ctrl:1
	ds_read_b128 v[72:75], v88 offset:9984
	v_pk_fma_f32 v[8:9], v[0:1], v[20:21], v[8:9]
	v_add_f32_dpp v4, v4, v4 quad_perm:[2,3,0,1] row_mask:0xf bank_mask:0xf bound_ctrl:1
	v_pk_fma_f32 v[10:11], v[2:3], v[22:23], v[10:11]
	s_nop 0
	v_add_f32_dpp v4, v4, v4 row_ror:4 row_mask:0xf bank_mask:0xf bound_ctrl:1
	ds_read_b128 v[76:79], v88 offset:10240
	s_nop 0
	v_add_f32_dpp v4, v4, v4 row_ror:8 row_mask:0xf bank_mask:0xf bound_ctrl:1
	v_pk_fma_f32 v[0:1], v[4:5], v[32:33], v[8:9] op_sel_hi:[0,1,1]
	v_pk_fma_f32 v[2:3], v[4:5], v[34:35], v[10:11] op_sel_hi:[0,1,1]
	v_pk_mul_f32 v[6:7], v[0:1], v[36:37]
	v_pk_fma_f32 v[6:7], v[2:3], v[38:39], v[6:7]
	v_add_f32_e32 v186, v6, v7
	ds_read2st64_b32 v[18:19], v90 offset0:41 offset1:47
	v_add_f32_dpp v198, v198, v198 row_shl:4 row_mask:0xf bank_mask:0x5 bound_ctrl:1
	v_add_f32_dpp v198, v202, v202 row_shr:4 row_mask:0xf bank_mask:0xa bound_ctrl:1
	v_add_f32_dpp v199, v199, v199 row_shl:4 row_mask:0xf bank_mask:0x5 bound_ctrl:1
	v_add_f32_dpp v199, v203, v203 row_shr:4 row_mask:0xf bank_mask:0xa bound_ctrl:1
	s_waitcnt vmcnt(18)
	ds_write_b128 v91, v[112:115] offset:24576
	s_waitcnt lgkmcnt(7)
	v_pk_mul_f32 v[4:5], v[0:1], v[48:49] neg_lo:[0,1] neg_hi:[0,1]
	ds_read_b128 v[92:95], v88 offset:11264
	v_pk_fma_f32 v[4:5], v[2:3], v[50:51], v[4:5] neg_lo:[0,1,0] neg_hi:[0,1,0]
	ds_read_b128 v[84:87], v88 offset:11008
	v_pk_mul_f32 v[8:9], v[44:45], v[16:17] op_sel:[0,1] op_sel_hi:[1,1]
	v_add_f32_e32 v4, v4, v5
	ds_read_b128 v[80:83], v88 offset:10752
	v_pk_mul_f32 v[10:11], v[46:47], v[16:17] op_sel:[0,1] op_sel_hi:[1,1]
	v_add_f32_dpp v4, v4, v4 quad_perm:[1,0,3,2] row_mask:0xf bank_mask:0xf bound_ctrl:1
	ds_read_b128 v[96:99], v88 offset:11520
	v_pk_fma_f32 v[8:9], v[0:1], v[40:41], v[8:9]
	v_add_f32_dpp v4, v4, v4 quad_perm:[2,3,0,1] row_mask:0xf bank_mask:0xf bound_ctrl:1
	v_pk_fma_f32 v[10:11], v[2:3], v[42:43], v[10:11]
	s_nop 0
	v_add_f32_dpp v4, v4, v4 row_ror:4 row_mask:0xf bank_mask:0xf bound_ctrl:1
	ds_read_b128 v[100:103], v88 offset:11776
	s_nop 0
	v_add_f32_dpp v4, v4, v4 row_ror:8 row_mask:0xf bank_mask:0xf bound_ctrl:1
	v_pk_fma_f32 v[0:1], v[4:5], v[52:53], v[8:9] op_sel_hi:[0,1,1]
	v_pk_fma_f32 v[2:3], v[4:5], v[54:55], v[10:11] op_sel_hi:[0,1,1]
	v_pk_mul_f32 v[6:7], v[0:1], v[56:57]
	v_pk_fma_f32 v[6:7], v[2:3], v[58:59], v[6:7]
	v_add_f32_e32 v187, v6, v7
	v_add_f32_dpp v200, v200, v200 row_shl:4 row_mask:0xf bank_mask:0x5 bound_ctrl:1
	v_add_f32_dpp v200, v204, v204 row_shr:4 row_mask:0xf bank_mask:0xa bound_ctrl:1
	v_add_f32_dpp v201, v201, v201 row_shl:4 row_mask:0xf bank_mask:0x5 bound_ctrl:1
	v_add_f32_dpp v201, v205, v205 row_shr:4 row_mask:0xf bank_mask:0xa bound_ctrl:1
	ds_write_b128 v91, v[116:119] offset:25600
	ds_write_b32 v91, v171 offset:25856
	s_waitcnt lgkmcnt(8)
	v_pk_mul_f32 v[4:5], v[0:1], v[68:69] neg_lo:[0,1] neg_hi:[0,1]
	ds_read_b128 v[28:31], v88 offset:12800
	v_pk_fma_f32 v[4:5], v[2:3], v[70:71], v[4:5] neg_lo:[0,1,0] neg_hi:[0,1,0]
	ds_read_b128 v[24:27], v88 offset:12544
	v_pk_mul_f32 v[8:9], v[64:65], v[18:19] op_sel_hi:[1,0]
	v_add_f32_e32 v4, v4, v5
	ds_read_b128 v[20:23], v88 offset:12288
	v_pk_mul_f32 v[10:11], v[66:67], v[18:19] op_sel_hi:[1,0]
	v_add_f32_dpp v4, v4, v4 quad_perm:[1,0,3,2] row_mask:0xf bank_mask:0xf bound_ctrl:1
	ds_read_b128 v[32:35], v88 offset:13056
	v_pk_fma_f32 v[8:9], v[0:1], v[60:61], v[8:9]
	v_add_f32_dpp v4, v4, v4 quad_perm:[2,3,0,1] row_mask:0xf bank_mask:0xf bound_ctrl:1
	v_pk_fma_f32 v[10:11], v[2:3], v[62:63], v[10:11]
	s_nop 0
	v_add_f32_dpp v4, v4, v4 row_ror:4 row_mask:0xf bank_mask:0xf bound_ctrl:1
	ds_read_b128 v[36:39], v88 offset:13312
	s_nop 0
	v_add_f32_dpp v4, v4, v4 row_ror:8 row_mask:0xf bank_mask:0xf bound_ctrl:1
	v_pk_fma_f32 v[0:1], v[4:5], v[72:73], v[8:9] op_sel_hi:[0,1,1]
	v_pk_fma_f32 v[2:3], v[4:5], v[74:75], v[10:11] op_sel_hi:[0,1,1]
	v_pk_mul_f32 v[6:7], v[0:1], v[76:77]
	v_pk_fma_f32 v[6:7], v[2:3], v[78:79], v[6:7]
	v_add_f32_e32 v188, v6, v7
	ds_read2st64_b32 v[16:17], v90 offset0:53 offset1:59
	v_add_f32_dpp v198, v198, v198 quad_perm:[1,0,3,2] row_mask:0xf bank_mask:0xf bound_ctrl:1
	v_add_f32_dpp v199, v199, v199 quad_perm:[1,0,3,2] row_mask:0xf bank_mask:0xf bound_ctrl:1
	v_cndmask_b32_e64 v198, v198, v199, s[30:31]
	v_lshlrev_b32_e32 v176, 16, v152
	v_and_b32_e32 v177, 0xffff0000, v152
	s_waitcnt lgkmcnt(8)
	v_pk_mul_f32 v[4:5], v[0:1], v[92:93] neg_lo:[0,1] neg_hi:[0,1]
	ds_read_b128 v[48:51], v88 offset:14336
	v_pk_fma_f32 v[4:5], v[2:3], v[94:95], v[4:5] neg_lo:[0,1,0] neg_hi:[0,1,0]
	ds_read_b128 v[44:47], v88 offset:14080
	v_pk_mul_f32 v[8:9], v[84:85], v[18:19] op_sel:[0,1] op_sel_hi:[1,1]
	v_add_f32_e32 v4, v4, v5
	ds_read_b128 v[40:43], v88 offset:13824
	v_pk_mul_f32 v[10:11], v[86:87], v[18:19] op_sel:[0,1] op_sel_hi:[1,1]
	v_add_f32_dpp v4, v4, v4 quad_perm:[1,0,3,2] row_mask:0xf bank_mask:0xf bound_ctrl:1
	ds_read_b128 v[52:55], v88 offset:14592
	v_pk_fma_f32 v[8:9], v[0:1], v[80:81], v[8:9]
	v_add_f32_dpp v4, v4, v4 quad_perm:[2,3,0,1] row_mask:0xf bank_mask:0xf bound_ctrl:1
	v_pk_fma_f32 v[10:11], v[2:3], v[82:83], v[10:11]
	s_nop 0
	v_add_f32_dpp v4, v4, v4 row_ror:4 row_mask:0xf bank_mask:0xf bound_ctrl:1
	ds_read_b128 v[56:59], v88 offset:14848
	s_nop 0
	v_add_f32_dpp v4, v4, v4 row_ror:8 row_mask:0xf bank_mask:0xf bound_ctrl:1
	v_pk_fma_f32 v[0:1], v[4:5], v[96:97], v[8:9] op_sel_hi:[0,1,1]
	v_pk_fma_f32 v[2:3], v[4:5], v[98:99], v[10:11] op_sel_hi:[0,1,1]
	v_pk_mul_f32 v[6:7], v[0:1], v[100:101]
	v_pk_fma_f32 v[6:7], v[2:3], v[102:103], v[6:7]
	v_add_f32_e32 v189, v6, v7
	v_add_f32_dpp v200, v200, v200 quad_perm:[1,0,3,2] row_mask:0xf bank_mask:0xf bound_ctrl:1
	v_add_f32_dpp v201, v201, v201 quad_perm:[1,0,3,2] row_mask:0xf bank_mask:0xf bound_ctrl:1
	v_cndmask_b32_e64 v200, v200, v201, s[30:31]
	v_lshlrev_b32_e32 v178, 16, v153
	v_and_b32_e32 v179, 0xffff0000, v153
	s_waitcnt lgkmcnt(5)
	v_pk_mul_f32 v[4:5], v[0:1], v[28:29] neg_lo:[0,1] neg_hi:[0,1]
	ds_read_b128 v[68:71], v88 offset:15872
	v_pk_fma_f32 v[4:5], v[2:3], v[30:31], v[4:5] neg_lo:[0,1,0] neg_hi:[0,1,0]
	ds_read_b128 v[64:67], v88 offset:15616
	v_pk_mul_f32 v[8:9], v[24:25], v[16:17] op_sel_hi:[1,0]
	v_add_f32_e32 v4, v4, v5
	ds_read_b128 v[60:63], v88 offset:15360
	v_pk_mul_f32 v[10:11], v[26:27], v[16:17] op_sel_hi:[1,0]
	v_add_f32_dpp v4, v4, v4 quad_perm:[1,0,3,2] row_mask:0xf bank_mask:0xf bound_ctrl:1
	ds_read_b128 v[72:75], v88 offset:16128
	v_pk_fma_f32 v[8:9], v[0:1], v[20:21], v[8:9]
	v_add_f32_dpp v4, v4, v4 quad_perm:[2,3,0,1] row_mask:0xf bank_mask:0xf bound_ctrl:1
	v_pk_fma_f32 v[10:11], v[2:3], v[22:23], v[10:11]
	s_nop 0
	v_add_f32_dpp v4, v4, v4 row_ror:4 row_mask:0xf bank_mask:0xf bound_ctrl:1
	ds_read_b128 v[76:79], v88 offset:16384
	s_nop 0
	v_add_f32_dpp v4, v4, v4 row_ror:8 row_mask:0xf bank_mask:0xf bound_ctrl:1
	v_pk_fma_f32 v[0:1], v[4:5], v[32:33], v[8:9] op_sel_hi:[0,1,1]
	v_pk_fma_f32 v[2:3], v[4:5], v[34:35], v[10:11] op_sel_hi:[0,1,1]
	v_pk_mul_f32 v[6:7], v[0:1], v[36:37]
	v_pk_fma_f32 v[6:7], v[2:3], v[38:39], v[6:7]
	v_add_f32_e32 v190, v6, v7
	ds_read2st64_b32 v[18:19], v90 offset0:65 offset1:71
	v_add_f32_dpp v198, v198, v198 quad_perm:[2,3,0,1] row_mask:0xf bank_mask:0xf bound_ctrl:1
	v_add_f32_dpp v200, v200, v200 quad_perm:[2,3,0,1] row_mask:0xf bank_mask:0xf bound_ctrl:1
	v_cndmask_b32_e64 v214, v198, v200, s[34:35]
	v_cvt_pk_bf16_f32 v214, v214, v214
	ds_write_b128 v91, v[176:179] offset:24832
	v_lshlrev_b32_e32 v176, 16, v154
	s_waitcnt lgkmcnt(7)
	v_pk_mul_f32 v[4:5], v[0:1], v[48:49] neg_lo:[0,1] neg_hi:[0,1]
	ds_read_b128 v[92:95], v88 offset:17408
	v_pk_fma_f32 v[4:5], v[2:3], v[50:51], v[4:5] neg_lo:[0,1,0] neg_hi:[0,1,0]
	ds_read_b128 v[84:87], v88 offset:17152
	v_pk_mul_f32 v[8:9], v[44:45], v[16:17] op_sel:[0,1] op_sel_hi:[1,1]
	v_add_f32_e32 v4, v4, v5
	ds_read_b128 v[80:83], v88 offset:16896
	v_pk_mul_f32 v[10:11], v[46:47], v[16:17] op_sel:[0,1] op_sel_hi:[1,1]
	v_add_f32_dpp v4, v4, v4 quad_perm:[1,0,3,2] row_mask:0xf bank_mask:0xf bound_ctrl:1
	ds_read_b128 v[96:99], v88 offset:17664
	v_pk_fma_f32 v[8:9], v[0:1], v[40:41], v[8:9]
	v_add_f32_dpp v4, v4, v4 quad_perm:[2,3,0,1] row_mask:0xf bank_mask:0xf bound_ctrl:1
	v_pk_fma_f32 v[10:11], v[2:3], v[42:43], v[10:11]
	s_nop 0
	v_add_f32_dpp v4, v4, v4 row_ror:4 row_mask:0xf bank_mask:0xf bound_ctrl:1
	ds_read_b128 v[100:103], v88 offset:17920
	s_nop 0
	v_add_f32_dpp v4, v4, v4 row_ror:8 row_mask:0xf bank_mask:0xf bound_ctrl:1
	v_pk_fma_f32 v[0:1], v[4:5], v[52:53], v[8:9] op_sel_hi:[0,1,1]
	v_pk_fma_f32 v[2:3], v[4:5], v[54:55], v[10:11] op_sel_hi:[0,1,1]
	v_pk_mul_f32 v[6:7], v[0:1], v[56:57]
	v_pk_fma_f32 v[6:7], v[2:3], v[58:59], v[6:7]
	v_add_f32_e32 v191, v6, v7
	s_cmp_eq_u32 s28, 0
	s_cbranch_scc1 .Lls0_noy
	global_store_short v145, v214, s[22:23]
	v_add_u32_e32 v145, s26, v145
.Lls0_noy:
	v_and_b32_e32 v177, 0xffff0000, v154
	v_lshlrev_b32_e32 v178, 16, v155
	s_waitcnt lgkmcnt(6)
	v_pk_mul_f32 v[4:5], v[0:1], v[68:69] neg_lo:[0,1] neg_hi:[0,1]
	ds_read_b128 v[28:31], v88 offset:18944
	v_pk_fma_f32 v[4:5], v[2:3], v[70:71], v[4:5] neg_lo:[0,1,0] neg_hi:[0,1,0]
	ds_read_b128 v[24:27], v88 offset:18688
	v_pk_mul_f32 v[8:9], v[64:65], v[18:19] op_sel_hi:[1,0]
	v_add_f32_e32 v4, v4, v5
	ds_read_b128 v[20:23], v88 offset:18432
	v_pk_mul_f32 v[10:11], v[66:67], v[18:19] op_sel_hi:[1,0]
	v_add_f32_dpp v4, v4, v4 quad_perm:[1,0,3,2] row_mask:0xf bank_mask:0xf bound_ctrl:1
	ds_read_b128 v[32:35], v88 offset:19200
	v_pk_fma_f32 v[8:9], v[0:1], v[60:61], v[8:9]
	v_add_f32_dpp v4, v4, v4 quad_perm:[2,3,0,1] row_mask:0xf bank_mask:0xf bound_ctrl:1
	v_pk_fma_f32 v[10:11], v[2:3], v[62:63], v[10:11]
	s_nop 0
	v_add_f32_dpp v4, v4, v4 row_ror:4 row_mask:0xf bank_mask:0xf bound_ctrl:1
	ds_read_b128 v[36:39], v88 offset:19456
	s_nop 0
	v_add_f32_dpp v4, v4, v4 row_ror:8 row_mask:0xf bank_mask:0xf bound_ctrl:1
	v_pk_fma_f32 v[0:1], v[4:5], v[72:73], v[8:9] op_sel_hi:[0,1,1]
	v_pk_fma_f32 v[2:3], v[4:5], v[74:75], v[10:11] op_sel_hi:[0,1,1]
	v_pk_mul_f32 v[6:7], v[0:1], v[76:77]
	v_pk_fma_f32 v[6:7], v[2:3], v[78:79], v[6:7]
	v_add_f32_e32 v192, v6, v7
	ds_read2st64_b32 v[16:17], v90 offset0:77 offset1:83
	v_and_b32_e32 v179, 0xffff0000, v155
	ds_write_b128 v91, v[176:179] offset:25088
	s_waitcnt lgkmcnt(7)
	v_pk_mul_f32 v[4:5], v[0:1], v[92:93] neg_lo:[0,1] neg_hi:[0,1]
	ds_read_b128 v[48:51], v88 offset:20480
	v_pk_fma_f32 v[4:5], v[2:3], v[94:95], v[4:5] neg_lo:[0,1,0] neg_hi:[0,1,0]
	ds_read_b128 v[44:47], v88 offset:20224
	v_pk_mul_f32 v[8:9], v[84:85], v[18:19] op_sel:[0,1] op_sel_hi:[1,1]
	v_add_f32_e32 v4, v4, v5
	ds_read_b128 v[40:43], v88 offset:19968
	v_pk_mul_f32 v[10:11], v[86:87], v[18:19] op_sel:[0,1] op_sel_hi:[1,1]
	v_add_f32_dpp v4, v4, v4 quad_perm:[1,0,3,2] row_mask:0xf bank_mask:0xf bound_ctrl:1
	ds_read_b128 v[52:55], v88 offset:20736
	v_pk_fma_f32 v[8:9], v[0:1], v[80:81], v[8:9]
	v_add_f32_dpp v4, v4, v4 quad_perm:[2,3,0,1] row_mask:0xf bank_mask:0xf bound_ctrl:1
	v_pk_fma_f32 v[10:11], v[2:3], v[82:83], v[10:11]
	s_nop 0
	v_add_f32_dpp v4, v4, v4 row_ror:4 row_mask:0xf bank_mask:0xf bound_ctrl:1
	ds_read_b128 v[56:59], v88 offset:20992
	s_nop 0
	v_add_f32_dpp v4, v4, v4 row_ror:8 row_mask:0xf bank_mask:0xf bound_ctrl:1
	v_pk_fma_f32 v[0:1], v[4:5], v[96:97], v[8:9] op_sel_hi:[0,1,1]
	v_pk_fma_f32 v[2:3], v[4:5], v[98:99], v[10:11] op_sel_hi:[0,1,1]
	v_pk_mul_f32 v[6:7], v[0:1], v[100:101]
	v_pk_fma_f32 v[6:7], v[2:3], v[102:103], v[6:7]
	v_add_f32_e32 v193, v6, v7
	v_lshlrev_b32_e32 v176, 16, v156
	v_and_b32_e32 v177, 0xffff0000, v156
	s_waitcnt lgkmcnt(6)
	v_pk_mul_f32 v[4:5], v[0:1], v[28:29] neg_lo:[0,1] neg_hi:[0,1]
	ds_read_b128 v[68:71], v88 offset:22016
	v_pk_fma_f32 v[4:5], v[2:3], v[30:31], v[4:5] neg_lo:[0,1,0] neg_hi:[0,1,0]
	ds_read_b128 v[64:67], v88 offset:21760
	v_pk_mul_f32 v[8:9], v[24:25], v[16:17] op_sel_hi:[1,0]
	v_add_f32_e32 v4, v4, v5
	ds_read_b128 v[60:63], v88 offset:21504
	v_pk_mul_f32 v[10:11], v[26:27], v[16:17] op_sel_hi:[1,0]
	v_add_f32_dpp v4, v4, v4 quad_perm:[1,0,3,2] row_mask:0xf bank_mask:0xf bound_ctrl:1
	ds_read_b128 v[72:75], v88 offset:22272
	v_pk_fma_f32 v[8:9], v[0:1], v[20:21], v[8:9]
	v_add_f32_dpp v4, v4, v4 quad_perm:[2,3,0,1] row_mask:0xf bank_mask:0xf bound_ctrl:1
	v_pk_fma_f32 v[10:11], v[2:3], v[22:23], v[10:11]
	s_nop 0
	v_add_f32_dpp v4, v4, v4 row_ror:4 row_mask:0xf bank_mask:0xf bound_ctrl:1
	ds_read_b128 v[76:79], v88 offset:22528
	s_nop 0
	v_add_f32_dpp v4, v4, v4 row_ror:8 row_mask:0xf bank_mask:0xf bound_ctrl:1
	v_pk_fma_f32 v[0:1], v[4:5], v[32:33], v[8:9] op_sel_hi:[0,1,1]
	v_pk_fma_f32 v[2:3], v[4:5], v[34:35], v[10:11] op_sel_hi:[0,1,1]
	v_pk_mul_f32 v[6:7], v[0:1], v[36:37]
	v_pk_fma_f32 v[6:7], v[2:3], v[38:39], v[6:7]
	v_add_f32_e32 v194, v6, v7
	ds_read2st64_b32 v[18:19], v90 offset0:89 offset1:95
	v_lshlrev_b32_e32 v178, 16, v157
	v_and_b32_e32 v179, 0xffff0000, v157
	ds_write_b128 v91, v[176:179] offset:25344
	s_waitcnt lgkmcnt(7)
	v_pk_mul_f32 v[4:5], v[0:1], v[48:49] neg_lo:[0,1] neg_hi:[0,1]
	ds_read_b128 v[92:95], v88 offset:23552
	v_pk_fma_f32 v[4:5], v[2:3], v[50:51], v[4:5] neg_lo:[0,1,0] neg_hi:[0,1,0]
	ds_read_b128 v[84:87], v88 offset:23296
	v_pk_mul_f32 v[8:9], v[44:45], v[16:17] op_sel:[0,1] op_sel_hi:[1,1]
	v_add_f32_e32 v4, v4, v5
	ds_read_b128 v[80:83], v88 offset:23040
	v_pk_mul_f32 v[10:11], v[46:47], v[16:17] op_sel:[0,1] op_sel_hi:[1,1]
	v_add_f32_dpp v4, v4, v4 quad_perm:[1,0,3,2] row_mask:0xf bank_mask:0xf bound_ctrl:1
	ds_read_b128 v[96:99], v88 offset:23808
	v_pk_fma_f32 v[8:9], v[0:1], v[40:41], v[8:9]
	v_add_f32_dpp v4, v4, v4 quad_perm:[2,3,0,1] row_mask:0xf bank_mask:0xf bound_ctrl:1
	v_pk_fma_f32 v[10:11], v[2:3], v[42:43], v[10:11]
	s_nop 0
	v_add_f32_dpp v4, v4, v4 row_ror:4 row_mask:0xf bank_mask:0xf bound_ctrl:1
	ds_read_b128 v[100:103], v88 offset:24064
	s_nop 0
	v_add_f32_dpp v4, v4, v4 row_ror:8 row_mask:0xf bank_mask:0xf bound_ctrl:1
	v_pk_fma_f32 v[0:1], v[4:5], v[52:53], v[8:9] op_sel_hi:[0,1,1]
	v_pk_fma_f32 v[2:3], v[4:5], v[54:55], v[10:11] op_sel_hi:[0,1,1]
	v_pk_mul_f32 v[6:7], v[0:1], v[56:57]
	v_pk_fma_f32 v[6:7], v[2:3], v[58:59], v[6:7]
	v_add_f32_e32 v195, v6, v7
	s_waitcnt lgkmcnt(0)
	s_barrier
	v_pk_mul_f32 v[4:5], v[0:1], v[68:69] neg_lo:[0,1] neg_hi:[0,1]
	ds_read_b128 v[28:31], v88 offset:25088
	v_pk_fma_f32 v[4:5], v[2:3], v[70:71], v[4:5] neg_lo:[0,1,0] neg_hi:[0,1,0]
	ds_read_b128 v[24:27], v88 offset:24832
	v_pk_mul_f32 v[8:9], v[64:65], v[18:19] op_sel_hi:[1,0]
	v_add_f32_e32 v4, v4, v5
	ds_read_b128 v[20:23], v88 offset:24576
	v_pk_mul_f32 v[10:11], v[66:67], v[18:19] op_sel_hi:[1,0]
	v_add_f32_dpp v4, v4, v4 quad_perm:[1,0,3,2] row_mask:0xf bank_mask:0xf bound_ctrl:1
	ds_read_b128 v[32:35], v88 offset:25344
	v_pk_fma_f32 v[8:9], v[0:1], v[60:61], v[8:9]
	v_add_f32_dpp v4, v4, v4 quad_perm:[2,3,0,1] row_mask:0xf bank_mask:0xf bound_ctrl:1
	v_pk_fma_f32 v[10:11], v[2:3], v[62:63], v[10:11]
	s_nop 0
	v_add_f32_dpp v4, v4, v4 row_ror:4 row_mask:0xf bank_mask:0xf bound_ctrl:1
	ds_read_b128 v[36:39], v88 offset:25600
	s_nop 0
	v_add_f32_dpp v4, v4, v4 row_ror:8 row_mask:0xf bank_mask:0xf bound_ctrl:1
	v_pk_fma_f32 v[0:1], v[4:5], v[72:73], v[8:9] op_sel_hi:[0,1,1]
	v_pk_fma_f32 v[2:3], v[4:5], v[74:75], v[10:11] op_sel_hi:[0,1,1]
	v_pk_mul_f32 v[6:7], v[0:1], v[76:77]
	v_pk_fma_f32 v[6:7], v[2:3], v[78:79], v[6:7]
	v_add_f32_e32 v196, v6, v7
	ds_read2st64_b32 v[16:17], v90 offset0:101 offset1:107
	s_waitcnt lgkmcnt(6)
	v_pk_mul_f32 v[4:5], v[0:1], v[92:93] neg_lo:[0,1] neg_hi:[0,1]
	ds_read_b128 v[48:51], v88 offset:26624
	v_pk_fma_f32 v[4:5], v[2:3], v[94:95], v[4:5] neg_lo:[0,1,0] neg_hi:[0,1,0]
	ds_read_b128 v[44:47], v88 offset:26368
	v_pk_mul_f32 v[8:9], v[84:85], v[18:19] op_sel:[0,1] op_sel_hi:[1,1]
	v_add_f32_e32 v4, v4, v5
	ds_read_b128 v[40:43], v88 offset:26112
	v_pk_mul_f32 v[10:11], v[86:87], v[18:19] op_sel:[0,1] op_sel_hi:[1,1]
	v_add_f32_dpp v4, v4, v4 quad_perm:[1,0,3,2] row_mask:0xf bank_mask:0xf bound_ctrl:1
	ds_read_b128 v[52:55], v88 offset:26880
	v_pk_fma_f32 v[8:9], v[0:1], v[80:81], v[8:9]
	v_add_f32_dpp v4, v4, v4 quad_perm:[2,3,0,1] row_mask:0xf bank_mask:0xf bound_ctrl:1
	v_pk_fma_f32 v[10:11], v[2:3], v[82:83], v[10:11]
	s_nop 0
	v_add_f32_dpp v4, v4, v4 row_ror:4 row_mask:0xf bank_mask:0xf bound_ctrl:1
	ds_read_b128 v[56:59], v88 offset:27136
	s_nop 0
	v_add_f32_dpp v4, v4, v4 row_ror:8 row_mask:0xf bank_mask:0xf bound_ctrl:1
	v_pk_fma_f32 v[0:1], v[4:5], v[96:97], v[8:9] op_sel_hi:[0,1,1]
	v_pk_fma_f32 v[2:3], v[4:5], v[98:99], v[10:11] op_sel_hi:[0,1,1]
	v_pk_mul_f32 v[6:7], v[0:1], v[100:101]
	v_pk_fma_f32 v[6:7], v[2:3], v[102:103], v[6:7]
	v_add_f32_e32 v197, v6, v7
	s_waitcnt lgkmcnt(5)
	v_pk_mul_f32 v[4:5], v[0:1], v[28:29] neg_lo:[0,1] neg_hi:[0,1]
	ds_read_b128 v[68:71], v88 offset:28160
	v_pk_fma_f32 v[4:5], v[2:3], v[30:31], v[4:5] neg_lo:[0,1,0] neg_hi:[0,1,0]
	ds_read_b128 v[64:67], v88 offset:27904
	v_pk_mul_f32 v[8:9], v[24:25], v[16:17] op_sel_hi:[1,0]
	v_add_f32_e32 v4, v4, v5
	ds_read_b128 v[60:63], v88 offset:27648
	v_pk_mul_f32 v[10:11], v[26:27], v[16:17] op_sel_hi:[1,0]
	v_add_f32_dpp v4, v4, v4 quad_perm:[1,0,3,2] row_mask:0xf bank_mask:0xf bound_ctrl:1
	ds_read_b128 v[72:75], v88 offset:28416
	v_pk_fma_f32 v[8:9], v[0:1], v[20:21], v[8:9]
	v_add_f32_dpp v4, v4, v4 quad_perm:[2,3,0,1] row_mask:0xf bank_mask:0xf bound_ctrl:1
	v_pk_fma_f32 v[10:11], v[2:3], v[22:23], v[10:11]
	s_nop 0
	v_add_f32_dpp v4, v4, v4 row_ror:4 row_mask:0xf bank_mask:0xf bound_ctrl:1
	ds_read_b128 v[76:79], v88 offset:28672
	s_nop 0
	v_add_f32_dpp v4, v4, v4 row_ror:8 row_mask:0xf bank_mask:0xf bound_ctrl:1
	v_pk_fma_f32 v[0:1], v[4:5], v[32:33], v[8:9] op_sel_hi:[0,1,1]
	v_pk_fma_f32 v[2:3], v[4:5], v[34:35], v[10:11] op_sel_hi:[0,1,1]
	v_pk_mul_f32 v[6:7], v[0:1], v[36:37]
	v_pk_fma_f32 v[6:7], v[2:3], v[38:39], v[6:7]
	v_add_f32_e32 v198, v6, v7
	ds_read2st64_b32 v[18:19], v90 offset0:113 offset1:119
	s_cmp_lt_u32 s28, 15
	s_cbranch_scc0 .Lls0_skip1
	global_load_dwordx4 v[112:115], v174, s[12:13]
	global_load_dwordx2 v[152:153], v175, s[14:15]
	global_load_dwordx2 v[154:155], v175, s[16:17]
	global_load_dwordx2 v[156:157], v175, s[18:19]
	global_load_dwordx4 v[116:119], v180, s[20:21]
	global_load_dword v171, v181, s[20:21]
	v_add_u32_e32 v174, s25, v174
	v_add_u32_e32 v175, s26, v175
	v_add_u32_e32 v180, s27, v180
	v_add_u32_e32 v181, s27, v181
.Lls0_back1:
	v_add_f32_dpp v182, v182, v182 row_ror:8 row_mask:0xf bank_mask:0x3 bound_ctrl:1
	v_add_f32_dpp v182, v190, v190 row_ror:8 row_mask:0xf bank_mask:0xc bound_ctrl:1
	v_add_f32_dpp v183, v183, v183 row_ror:8 row_mask:0xf bank_mask:0x3 bound_ctrl:1
	v_add_f32_dpp v183, v191, v191 row_ror:8 row_mask:0xf bank_mask:0xc bound_ctrl:1
	s_waitcnt lgkmcnt(6)
	v_pk_mul_f32 v[4:5], v[0:1], v[48:49] neg_lo:[0,1] neg_hi:[0,1]
	ds_read_b128 v[92:95], v88 offset:29696
	v_pk_fma_f32 v[4:5], v[2:3], v[50:51], v[4:5] neg_lo:[0,1,0] neg_hi:[0,1,0]
	ds_read_b128 v[84:87], v88 offset:29440
	v_pk_mul_f32 v[8:9], v[44:45], v[16:17] op_sel:[0,1] op_sel_hi:[1,1]
	v_add_f32_e32 v4, v4, v5
	ds_read_b128 v[80:83], v88 offset:29184
	v_pk_mul_f32 v[10:11], v[46:47], v[16:17] op_sel:[0,1] op_sel_hi:[1,1]
	v_add_f32_dpp v4, v4, v4 quad_perm:[1,0,3,2] row_mask:0xf bank_mask:0xf bound_ctrl:1
	ds_read_b128 v[96:99], v88 offset:29952
	v_pk_fma_f32 v[8:9], v[0:1], v[40:41], v[8:9]
	v_add_f32_dpp v4, v4, v4 quad_perm:[2,3,0,1] row_mask:0xf bank_mask:0xf bound_ctrl:1
	v_pk_fma_f32 v[10:11], v[2:3], v[42:43], v[10:11]
	s_nop 0
	v_add_f32_dpp v4, v4, v4 row_ror:4 row_mask:0xf bank_mask:0xf bound_ctrl:1
	ds_read_b128 v[100:103], v88 offset:30208
	s_nop 0
	v_add_f32_dpp v4, v4, v4 row_ror:8 row_mask:0xf bank_mask:0xf bound_ctrl:1
	v_pk_fma_f32 v[0:1], v[4:5], v[52:53], v[8:9] op_sel_hi:[0,1,1]
	v_pk_fma_f32 v[2:3], v[4:5], v[54:55], v[10:11] op_sel_hi:[0,1,1]
	v_pk_mul_f32 v[6:7], v[0:1], v[56:57]
	v_pk_fma_f32 v[6:7], v[2:3], v[58:59], v[6:7]
	v_add_f32_e32 v199, v6, v7
	v_add_f32_dpp v184, v184, v184 row_ror:8 row_mask:0xf bank_mask:0x3 bound_ctrl:1
	v_add_f32_dpp v184, v192, v192 row_ror:8 row_mask:0xf bank_mask:0xc bound_ctrl:1
	v_add_f32_dpp v185, v185, v185 row_ror:8 row_mask:0xf bank_mask:0x3 bound_ctrl:1
	v_add_f32_dpp v185, v193, v193 row_ror:8 row_mask:0xf bank_mask:0xc bound_ctrl:1
	s_waitcnt lgkmcnt(5)
	v_pk_mul_f32 v[4:5], v[0:1], v[68:69] neg_lo:[0,1] neg_hi:[0,1]
	ds_read_b128 v[28:31], v88 offset:31232
	v_pk_fma_f32 v[4:5], v[2:3], v[70:71], v[4:5] neg_lo:[0,1,0] neg_hi:[0,1,0]
	ds_read_b128 v[24:27], v88 offset:30976
	v_pk_mul_f32 v[8:9], v[64:65], v[18:19] op_sel_hi:[1,0]
	v_add_f32_e32 v4, v4, v5
	ds_read_b128 v[20:23], v88 offset:30720
	v_pk_mul_f32 v[10:11], v[66:67], v[18:19] op_sel_hi:[1,0]
	v_add_f32_dpp v4, v4, v4 quad_perm:[1,0,3,2] row_mask:0xf bank_mask:0xf bound_ctrl:1
	ds_read_b128 v[32:35], v88 offset:31488
	v_pk_fma_f32 v[8:9], v[0:1], v[60:61], v[8:9]
	v_add_f32_dpp v4, v4, v4 quad_perm:[2,3,0,1] row_mask:0xf bank_mask:0xf bound_ctrl:1
	v_pk_fma_f32 v[10:11], v[2:3], v[62:63], v[10:11]
	s_nop 0
	v_add_f32_dpp v4, v4, v4 row_ror:4 row_mask:0xf bank_mask:0xf bound_ctrl:1
	ds_read_b128 v[36:39], v88 offset:31744
	s_nop 0
	v_add_f32_dpp v4, v4, v4 row_ror:8 row_mask:0xf bank_mask:0xf bound_ctrl:1
	v_pk_fma_f32 v[0:1], v[4:5], v[72:73], v[8:9] op_sel_hi:[0,1,1]
	v_pk_fma_f32 v[2:3], v[4:5], v[74:75], v[10:11] op_sel_hi:[0,1,1]
	v_pk_mul_f32 v[6:7], v[0:1], v[76:77]
	v_pk_fma_f32 v[6:7], v[2:3], v[78:79], v[6:7]
	v_add_f32_e32 v200, v6, v7
	ds_read2st64_b32 v[16:17], v90 offset0:125 offset1:131
	v_add_f32_dpp v186, v186, v186 row_ror:8 row_mask:0xf bank_mask:0x3 bound_ctrl:1
	v_add_f32_dpp v186, v194, v194 row_ror:8 row_mask:0xf bank_mask:0xc bound_ctrl:1
	v_add_f32_dpp v187, v187, v187 row_ror:8 row_mask:0xf bank_mask:0x3 bound_ctrl:1
	v_add_f32_dpp v187, v195, v195 row_ror:8 row_mask:0xf bank_mask:0xc bound_ctrl:1
	s_waitcnt lgkmcnt(6)
	v_pk_mul_f32 v[4:5], v[0:1], v[92:93] neg_lo:[0,1] neg_hi:[0,1]
	ds_read_b128 v[48:51], v88 offset:32768
	v_pk_fma_f32 v[4:5], v[2:3], v[94:95], v[4:5] neg_lo:[0,1,0] neg_hi:[0,1,0]
	ds_read_b128 v[44:47], v88 offset:32512
	v_pk_mul_f32 v[8:9], v[84:85], v[18:19] op_sel:[0,1] op_sel_hi:[1,1]
	v_add_f32_e32 v4, v4, v5
	ds_read_b128 v[40:43], v88 offset:32256
	v_pk_mul_f32 v[10:11], v[86:87], v[18:19] op_sel:[0,1] op_sel_hi:[1,1]
	v_add_f32_dpp v4, v4, v4 quad_perm:[1,0,3,2] row_mask:0xf bank_mask:0xf bound_ctrl:1
	ds_read_b128 v[52:55], v88 offset:33024
	v_pk_fma_f32 v[8:9], v[0:1], v[80:81], v[8:9]
	v_add_f32_dpp v4, v4, v4 quad_perm:[2,3,0,1] row_mask:0xf bank_mask:0xf bound_ctrl:1
	v_pk_fma_f32 v[10:11], v[2:3], v[82:83], v[10:11]
	s_nop 0
	v_add_f32_dpp v4, v4, v4 row_ror:4 row_mask:0xf bank_mask:0xf bound_ctrl:1
	ds_read_b128 v[56:59], v88 offset:33280
	s_nop 0
	v_add_f32_dpp v4, v4, v4 row_ror:8 row_mask:0xf bank_mask:0xf bound_ctrl:1
	v_pk_fma_f32 v[0:1], v[4:5], v[96:97], v[8:9] op_sel_hi:[0,1,1]
	v_pk_fma_f32 v[2:3], v[4:5], v[98:99], v[10:11] op_sel_hi:[0,1,1]
	v_pk_mul_f32 v[6:7], v[0:1], v[100:101]
	v_pk_fma_f32 v[6:7], v[2:3], v[102:103], v[6:7]
	v_add_f32_e32 v201, v6, v7
	v_add_f32_dpp v188, v188, v188 row_ror:8 row_mask:0xf bank_mask:0x3 bound_ctrl:1
	v_add_f32_dpp v188, v196, v196 row_ror:8 row_mask:0xf bank_mask:0xc bound_ctrl:1
	v_add_f32_dpp v189, v189, v189 row_ror:8 row_mask:0xf bank_mask:0x3 bound_ctrl:1
	v_add_f32_dpp v189, v197, v197 row_ror:8 row_mask:0xf bank_mask:0xc bound_ctrl:1
	s_waitcnt lgkmcnt(5)
	v_pk_mul_f32 v[4:5], v[0:1], v[28:29] neg_lo:[0,1] neg_hi:[0,1]
	ds_read_b128 v[68:71], v88 offset:34304
	v_pk_fma_f32 v[4:5], v[2:3], v[30:31], v[4:5] neg_lo:[0,1,0] neg_hi:[0,1,0]
	ds_read_b128 v[64:67], v88 offset:34048
	v_pk_mul_f32 v[8:9], v[24:25], v[16:17] op_sel_hi:[1,0]
	v_add_f32_e32 v4, v4, v5
	ds_read_b128 v[60:63], v88 offset:33792
	v_pk_mul_f32 v[10:11], v[26:27], v[16:17] op_sel_hi:[1,0]
	v_add_f32_dpp v4, v4, v4 quad_perm:[1,0,3,2] row_mask:0xf bank_mask:0xf bound_ctrl:1
	ds_read_b128 v[72:75], v88 offset:34560
	v_pk_fma_f32 v[8:9], v[0:1], v[20:21], v[8:9]
	v_add_f32_dpp v4, v4, v4 quad_perm:[2,3,0,1] row_mask:0xf bank_mask:0xf bound_ctrl:1
	v_pk_fma_f32 v[10:11], v[2:3], v[22:23], v[10:11]
	s_nop 0
	v_add_f32_dpp v4, v4, v4 row_ror:4 row_mask:0xf bank_mask:0xf bound_ctrl:1
	ds_read_b128 v[76:79], v88 offset:34816
	s_nop 0
	v_add_f32_dpp v4, v4, v4 row_ror:8 row_mask:0xf bank_mask:0xf bound_ctrl:1
	v_pk_fma_f32 v[0:1], v[4:5], v[32:33], v[8:9] op_sel_hi:[0,1,1]
	v_pk_fma_f32 v[2:3], v[4:5], v[34:35], v[10:11] op_sel_hi:[0,1,1]
	v_pk_mul_f32 v[6:7], v[0:1], v[36:37]
	v_pk_fma_f32 v[6:7], v[2:3], v[38:39], v[6:7]
	v_add_f32_e32 v202, v6, v7
	ds_read2st64_b32 v[18:19], v90 offset0:137 offset1:143
	v_add_f32_dpp v182, v182, v182 row_shl:4 row_mask:0xf bank_mask:0x5 bound_ctrl:1
	v_add_f32_dpp v182, v186, v186 row_shr:4 row_mask:0xf bank_mask:0xa bound_ctrl:1
	v_add_f32_dpp v183, v183, v183 row_shl:4 row_mask:0xf bank_mask:0x5 bound_ctrl:1
	v_add_f32_dpp v183, v187, v187 row_shr:4 row_mask:0xf bank_mask:0xa bound_ctrl:1
	s_waitcnt vmcnt(18)
	ds_write_b128 v91, v[120:123] offset:0
	s_waitcnt lgkmcnt(7)
	v_pk_mul_f32 v[4:5], v[0:1], v[48:49] neg_lo:[0,1] neg_hi:[0,1]
	ds_read_b128 v[92:95], v88 offset:35840
	v_pk_fma_f32 v[4:5], v[2:3], v[50:51], v[4:5] neg_lo:[0,1,0] neg_hi:[0,1,0]
	ds_read_b128 v[84:87], v88 offset:35584
	v_pk_mul_f32 v[8:9], v[44:45], v[16:17] op_sel:[0,1] op_sel_hi:[1,1]
	v_add_f32_e32 v4, v4, v5
	ds_read_b128 v[80:83], v88 offset:35328
	v_pk_mul_f32 v[10:11], v[46:47], v[16:17] op_sel:[0,1] op_sel_hi:[1,1]
	v_add_f32_dpp v4, v4, v4 quad_perm:[1,0,3,2] row_mask:0xf bank_mask:0xf bound_ctrl:1
	ds_read_b128 v[96:99], v88 offset:36096
	v_pk_fma_f32 v[8:9], v[0:1], v[40:41], v[8:9]
	v_add_f32_dpp v4, v4, v4 quad_perm:[2,3,0,1] row_mask:0xf bank_mask:0xf bound_ctrl:1
	v_pk_fma_f32 v[10:11], v[2:3], v[42:43], v[10:11]
	s_nop 0
	v_add_f32_dpp v4, v4, v4 row_ror:4 row_mask:0xf bank_mask:0xf bound_ctrl:1
	ds_read_b128 v[100:103], v88 offset:36352
	s_nop 0
	v_add_f32_dpp v4, v4, v4 row_ror:8 row_mask:0xf bank_mask:0xf bound_ctrl:1
	v_pk_fma_f32 v[0:1], v[4:5], v[52:53], v[8:9] op_sel_hi:[0,1,1]
	v_pk_fma_f32 v[2:3], v[4:5], v[54:55], v[10:11] op_sel_hi:[0,1,1]
	v_pk_mul_f32 v[6:7], v[0:1], v[56:57]
	v_pk_fma_f32 v[6:7], v[2:3], v[58:59], v[6:7]
	v_add_f32_e32 v203, v6, v7
	v_add_f32_dpp v184, v184, v184 row_shl:4 row_mask:0xf bank_mask:0x5 bound_ctrl:1
	v_add_f32_dpp v184, v188, v188 row_shr:4 row_mask:0xf bank_mask:0xa bound_ctrl:1
	v_add_f32_dpp v185, v185, v185 row_shl:4 row_mask:0xf bank_mask:0x5 bound_ctrl:1
	v_add_f32_dpp v185, v189, v189 row_shr:4 row_mask:0xf bank_mask:0xa bound_ctrl:1
	ds_write_b128 v91, v[124:127] offset:1024
	ds_write_b32 v91, v172 offset:1280
	s_waitcnt lgkmcnt(8)
	v_pk_mul_f32 v[4:5], v[0:1], v[68:69] neg_lo:[0,1] neg_hi:[0,1]
	ds_read_b128 v[28:31], v88 offset:37376
	v_pk_fma_f32 v[4:5], v[2:3], v[70:71], v[4:5] neg_lo:[0,1,0] neg_hi:[0,1,0]
	ds_read_b128 v[24:27], v88 offset:37120
	v_pk_mul_f32 v[8:9], v[64:65], v[18:19] op_sel_hi:[1,0]
	v_add_f32_e32 v4, v4, v5
	ds_read_b128 v[20:23], v88 offset:36864
	v_pk_mul_f32 v[10:11], v[66:67], v[18:19] op_sel_hi:[1,0]
	v_add_f32_dpp v4, v4, v4 quad_perm:[1,0,3,2] row_mask:0xf bank_mask:0xf bound_ctrl:1
	ds_read_b128 v[32:35], v88 offset:37632
	v_pk_fma_f32 v[8:9], v[0:1], v[60:61], v[8:9]
	v_add_f32_dpp v4, v4, v4 quad_perm:[2,3,0,1] row_mask:0xf bank_mask:0xf bound_ctrl:1
	v_pk_fma_f32 v[10:11], v[2:3], v[62:63], v[10:11]
	s_nop 0
	v_add_f32_dpp v4, v4, v4 row_ror:4 row_mask:0xf bank_mask:0xf bound_ctrl:1
	ds_read_b128 v[36:39], v88 offset:37888
	s_nop 0
	v_add_f32_dpp v4, v4, v4 row_ror:8 row_mask:0xf bank_mask:0xf bound_ctrl:1
	v_pk_fma_f32 v[0:1], v[4:5], v[72:73], v[8:9] op_sel_hi:[0,1,1]
	v_pk_fma_f32 v[2:3], v[4:5], v[74:75], v[10:11] op_sel_hi:[0,1,1]
	v_pk_mul_f32 v[6:7], v[0:1], v[76:77]
	v_pk_fma_f32 v[6:7], v[2:3], v[78:79], v[6:7]
	v_add_f32_e32 v204, v6, v7
	ds_read2st64_b32 v[16:17], v90 offset0:149 offset1:155
	v_add_f32_dpp v182, v182, v182 quad_perm:[1,0,3,2] row_mask:0xf bank_mask:0xf bound_ctrl:1
	v_add_f32_dpp v183, v183, v183 quad_perm:[1,0,3,2] row_mask:0xf bank_mask:0xf bound_ctrl:1
	v_cndmask_b32_e64 v182, v182, v183, s[30:31]
	v_lshlrev_b32_e32 v176, 16, v158
	v_and_b32_e32 v177, 0xffff0000, v158
	s_waitcnt lgkmcnt(8)
	v_pk_mul_f32 v[4:5], v[0:1], v[92:93] neg_lo:[0,1] neg_hi:[0,1]
	ds_read_b128 v[48:51], v88 offset:38912
	v_pk_fma_f32 v[4:5], v[2:3], v[94:95], v[4:5] neg_lo:[0,1,0] neg_hi:[0,1,0]
	ds_read_b128 v[44:47], v88 offset:38656
	v_pk_mul_f32 v[8:9], v[84:85], v[18:19] op_sel:[0,1] op_sel_hi:[1,1]
	v_add_f32_e32 v4, v4, v5
	ds_read_b128 v[40:43], v88 offset:38400
	v_pk_mul_f32 v[10:11], v[86:87], v[18:19] op_sel:[0,1] op_sel_hi:[1,1]
	v_add_f32_dpp v4, v4, v4 quad_perm:[1,0,3,2] row_mask:0xf bank_mask:0xf bound_ctrl:1
	ds_read_b128 v[52:55], v88 offset:39168
	v_pk_fma_f32 v[8:9], v[0:1], v[80:81], v[8:9]
	v_add_f32_dpp v4, v4, v4 quad_perm:[2,3,0,1] row_mask:0xf bank_mask:0xf bound_ctrl:1
	v_pk_fma_f32 v[10:11], v[2:3], v[82:83], v[10:11]
	s_nop 0
	v_add_f32_dpp v4, v4, v4 row_ror:4 row_mask:0xf bank_mask:0xf bound_ctrl:1
	ds_read_b128 v[56:59], v88 offset:39424
	s_nop 0
	v_add_f32_dpp v4, v4, v4 row_ror:8 row_mask:0xf bank_mask:0xf bound_ctrl:1
	v_pk_fma_f32 v[0:1], v[4:5], v[96:97], v[8:9] op_sel_hi:[0,1,1]
	v_pk_fma_f32 v[2:3], v[4:5], v[98:99], v[10:11] op_sel_hi:[0,1,1]
	v_pk_mul_f32 v[6:7], v[0:1], v[100:101]
	v_pk_fma_f32 v[6:7], v[2:3], v[102:103], v[6:7]
	v_add_f32_e32 v205, v6, v7
	v_add_f32_dpp v184, v184, v184 quad_perm:[1,0,3,2] row_mask:0xf bank_mask:0xf bound_ctrl:1
	v_add_f32_dpp v185, v185, v185 quad_perm:[1,0,3,2] row_mask:0xf bank_mask:0xf bound_ctrl:1
	v_cndmask_b32_e64 v184, v184, v185, s[30:31]
	v_lshlrev_b32_e32 v178, 16, v159
	v_and_b32_e32 v179, 0xffff0000, v159
	s_waitcnt lgkmcnt(5)
	v_pk_mul_f32 v[4:5], v[0:1], v[28:29] neg_lo:[0,1] neg_hi:[0,1]
	ds_read_b128 v[68:71], v88 offset:40448
	v_pk_fma_f32 v[4:5], v[2:3], v[30:31], v[4:5] neg_lo:[0,1,0] neg_hi:[0,1,0]
	ds_read_b128 v[64:67], v88 offset:40192
	v_pk_mul_f32 v[8:9], v[24:25], v[16:17] op_sel_hi:[1,0]
	v_add_f32_e32 v4, v4, v5
	ds_read_b128 v[60:63], v88 offset:39936
	v_pk_mul_f32 v[10:11], v[26:27], v[16:17] op_sel_hi:[1,0]
	v_add_f32_dpp v4, v4, v4 quad_perm:[1,0,3,2] row_mask:0xf bank_mask:0xf bound_ctrl:1
	ds_read_b128 v[72:75], v88 offset:40704
	v_pk_fma_f32 v[8:9], v[0:1], v[20:21], v[8:9]
	v_add_f32_dpp v4, v4, v4 quad_perm:[2,3,0,1] row_mask:0xf bank_mask:0xf bound_ctrl:1
	v_pk_fma_f32 v[10:11], v[2:3], v[22:23], v[10:11]
	s_nop 0
	v_add_f32_dpp v4, v4, v4 row_ror:4 row_mask:0xf bank_mask:0xf bound_ctrl:1
	ds_read_b128 v[76:79], v88 offset:40960
	s_nop 0
	v_add_f32_dpp v4, v4, v4 row_ror:8 row_mask:0xf bank_mask:0xf bound_ctrl:1
	v_pk_fma_f32 v[0:1], v[4:5], v[32:33], v[8:9] op_sel_hi:[0,1,1]
	v_pk_fma_f32 v[2:3], v[4:5], v[34:35], v[10:11] op_sel_hi:[0,1,1]
	v_pk_mul_f32 v[6:7], v[0:1], v[36:37]
	v_pk_fma_f32 v[6:7], v[2:3], v[38:39], v[6:7]
	v_add_f32_e32 v206, v6, v7
	ds_read2st64_b32 v[18:19], v90 offset0:161 offset1:167
	v_add_f32_dpp v182, v182, v182 quad_perm:[2,3,0,1] row_mask:0xf bank_mask:0xf bound_ctrl:1
	v_add_f32_dpp v184, v184, v184 quad_perm:[2,3,0,1] row_mask:0xf bank_mask:0xf bound_ctrl:1
	v_cndmask_b32_e64 v214, v182, v184, s[34:35]
	v_cvt_pk_bf16_f32 v214, v214, v214
	ds_write_b128 v91, v[176:179] offset:256
	v_lshlrev_b32_e32 v176, 16, v160
	s_waitcnt lgkmcnt(7)
	v_pk_mul_f32 v[4:5], v[0:1], v[48:49] neg_lo:[0,1] neg_hi:[0,1]
	ds_read_b128 v[92:95], v88 offset:41984
	v_pk_fma_f32 v[4:5], v[2:3], v[50:51], v[4:5] neg_lo:[0,1,0] neg_hi:[0,1,0]
	ds_read_b128 v[84:87], v88 offset:41728
	v_pk_mul_f32 v[8:9], v[44:45], v[16:17] op_sel:[0,1] op_sel_hi:[1,1]
	v_add_f32_e32 v4, v4, v5
	ds_read_b128 v[80:83], v88 offset:41472
	v_pk_mul_f32 v[10:11], v[46:47], v[16:17] op_sel:[0,1] op_sel_hi:[1,1]
	v_add_f32_dpp v4, v4, v4 quad_perm:[1,0,3,2] row_mask:0xf bank_mask:0xf bound_ctrl:1
	ds_read_b128 v[96:99], v88 offset:42240
	v_pk_fma_f32 v[8:9], v[0:1], v[40:41], v[8:9]
	v_add_f32_dpp v4, v4, v4 quad_perm:[2,3,0,1] row_mask:0xf bank_mask:0xf bound_ctrl:1
	v_pk_fma_f32 v[10:11], v[2:3], v[42:43], v[10:11]
	s_nop 0
	v_add_f32_dpp v4, v4, v4 row_ror:4 row_mask:0xf bank_mask:0xf bound_ctrl:1
	ds_read_b128 v[100:103], v88 offset:42496
	s_nop 0
	v_add_f32_dpp v4, v4, v4 row_ror:8 row_mask:0xf bank_mask:0xf bound_ctrl:1
	v_pk_fma_f32 v[0:1], v[4:5], v[52:53], v[8:9] op_sel_hi:[0,1,1]
	v_pk_fma_f32 v[2:3], v[4:5], v[54:55], v[10:11] op_sel_hi:[0,1,1]
	v_pk_mul_f32 v[6:7], v[0:1], v[56:57]
	v_pk_fma_f32 v[6:7], v[2:3], v[58:59], v[6:7]
	v_add_f32_e32 v207, v6, v7
	global_store_short v145, v214, s[22:23]
	v_add_u32_e32 v145, s26, v145
	v_and_b32_e32 v177, 0xffff0000, v160
	v_lshlrev_b32_e32 v178, 16, v161
	s_waitcnt lgkmcnt(6)
	v_pk_mul_f32 v[4:5], v[0:1], v[68:69] neg_lo:[0,1] neg_hi:[0,1]
	ds_read_b128 v[28:31], v88 offset:43520
	v_pk_fma_f32 v[4:5], v[2:3], v[70:71], v[4:5] neg_lo:[0,1,0] neg_hi:[0,1,0]
	ds_read_b128 v[24:27], v88 offset:43264
	v_pk_mul_f32 v[8:9], v[64:65], v[18:19] op_sel_hi:[1,0]
	v_add_f32_e32 v4, v4, v5
	ds_read_b128 v[20:23], v88 offset:43008
	v_pk_mul_f32 v[10:11], v[66:67], v[18:19] op_sel_hi:[1,0]
	v_add_f32_dpp v4, v4, v4 quad_perm:[1,0,3,2] row_mask:0xf bank_mask:0xf bound_ctrl:1
	ds_read_b128 v[32:35], v88 offset:43776
	v_pk_fma_f32 v[8:9], v[0:1], v[60:61], v[8:9]
	v_add_f32_dpp v4, v4, v4 quad_perm:[2,3,0,1] row_mask:0xf bank_mask:0xf bound_ctrl:1
	v_pk_fma_f32 v[10:11], v[2:3], v[62:63], v[10:11]
	s_nop 0
	v_add_f32_dpp v4, v4, v4 row_ror:4 row_mask:0xf bank_mask:0xf bound_ctrl:1
	ds_read_b128 v[36:39], v88 offset:44032
	s_nop 0
	v_add_f32_dpp v4, v4, v4 row_ror:8 row_mask:0xf bank_mask:0xf bound_ctrl:1
	v_pk_fma_f32 v[0:1], v[4:5], v[72:73], v[8:9] op_sel_hi:[0,1,1]
	v_pk_fma_f32 v[2:3], v[4:5], v[74:75], v[10:11] op_sel_hi:[0,1,1]
	v_pk_mul_f32 v[6:7], v[0:1], v[76:77]
	v_pk_fma_f32 v[6:7], v[2:3], v[78:79], v[6:7]
	v_add_f32_e32 v208, v6, v7
	ds_read2st64_b32 v[16:17], v90 offset0:173 offset1:179
	v_and_b32_e32 v179, 0xffff0000, v161
	ds_write_b128 v91, v[176:179] offset:512
	s_waitcnt lgkmcnt(7)
	v_pk_mul_f32 v[4:5], v[0:1], v[92:93] neg_lo:[0,1] neg_hi:[0,1]
	ds_read_b128 v[48:51], v88 offset:45056
	v_pk_fma_f32 v[4:5], v[2:3], v[94:95], v[4:5] neg_lo:[0,1,0] neg_hi:[0,1,0]
	ds_read_b128 v[44:47], v88 offset:44800
	v_pk_mul_f32 v[8:9], v[84:85], v[18:19] op_sel:[0,1] op_sel_hi:[1,1]
	v_add_f32_e32 v4, v4, v5
	ds_read_b128 v[40:43], v88 offset:44544
	v_pk_mul_f32 v[10:11], v[86:87], v[18:19] op_sel:[0,1] op_sel_hi:[1,1]
	v_add_f32_dpp v4, v4, v4 quad_perm:[1,0,3,2] row_mask:0xf bank_mask:0xf bound_ctrl:1
	ds_read_b128 v[52:55], v88 offset:45312
	v_pk_fma_f32 v[8:9], v[0:1], v[80:81], v[8:9]
	v_add_f32_dpp v4, v4, v4 quad_perm:[2,3,0,1] row_mask:0xf bank_mask:0xf bound_ctrl:1
	v_pk_fma_f32 v[10:11], v[2:3], v[82:83], v[10:11]
	s_nop 0
	v_add_f32_dpp v4, v4, v4 row_ror:4 row_mask:0xf bank_mask:0xf bound_ctrl:1
	ds_read_b128 v[56:59], v88 offset:45568
	s_nop 0
	v_add_f32_dpp v4, v4, v4 row_ror:8 row_mask:0xf bank_mask:0xf bound_ctrl:1
	v_pk_fma_f32 v[0:1], v[4:5], v[96:97], v[8:9] op_sel_hi:[0,1,1]
	v_pk_fma_f32 v[2:3], v[4:5], v[98:99], v[10:11] op_sel_hi:[0,1,1]
	v_pk_mul_f32 v[6:7], v[0:1], v[100:101]
	v_pk_fma_f32 v[6:7], v[2:3], v[102:103], v[6:7]
	v_add_f32_e32 v209, v6, v7
	v_lshlrev_b32_e32 v176, 16, v162
	v_and_b32_e32 v177, 0xffff0000, v162
	s_waitcnt lgkmcnt(6)
	v_pk_mul_f32 v[4:5], v[0:1], v[28:29] neg_lo:[0,1] neg_hi:[0,1]
	ds_read_b128 v[68:71], v88 offset:46592
	v_pk_fma_f32 v[4:5], v[2:3], v[30:31], v[4:5] neg_lo:[0,1,0] neg_hi:[0,1,0]
	ds_read_b128 v[64:67], v88 offset:46336
	v_pk_mul_f32 v[8:9], v[24:25], v[16:17] op_sel_hi:[1,0]
	v_add_f32_e32 v4, v4, v5
	ds_read_b128 v[60:63], v88 offset:46080
	v_pk_mul_f32 v[10:11], v[26:27], v[16:17] op_sel_hi:[1,0]
	v_add_f32_dpp v4, v4, v4 quad_perm:[1,0,3,2] row_mask:0xf bank_mask:0xf bound_ctrl:1
	ds_read_b128 v[72:75], v88 offset:46848
	v_pk_fma_f32 v[8:9], v[0:1], v[20:21], v[8:9]
	v_add_f32_dpp v4, v4, v4 quad_perm:[2,3,0,1] row_mask:0xf bank_mask:0xf bound_ctrl:1
	v_pk_fma_f32 v[10:11], v[2:3], v[22:23], v[10:11]
	s_nop 0
	v_add_f32_dpp v4, v4, v4 row_ror:4 row_mask:0xf bank_mask:0xf bound_ctrl:1
	ds_read_b128 v[76:79], v88 offset:47104
	s_nop 0
	v_add_f32_dpp v4, v4, v4 row_ror:8 row_mask:0xf bank_mask:0xf bound_ctrl:1
	v_pk_fma_f32 v[0:1], v[4:5], v[32:33], v[8:9] op_sel_hi:[0,1,1]
	v_pk_fma_f32 v[2:3], v[4:5], v[34:35], v[10:11] op_sel_hi:[0,1,1]
	v_pk_mul_f32 v[6:7], v[0:1], v[36:37]
	v_pk_fma_f32 v[6:7], v[2:3], v[38:39], v[6:7]
	v_add_f32_e32 v210, v6, v7
	ds_read2st64_b32 v[18:19], v90 offset0:185 offset1:191
	v_lshlrev_b32_e32 v178, 16, v163
	v_and_b32_e32 v179, 0xffff0000, v163
	ds_write_b128 v91, v[176:179] offset:768
	s_waitcnt lgkmcnt(7)
	v_pk_mul_f32 v[4:5], v[0:1], v[48:49] neg_lo:[0,1] neg_hi:[0,1]
	ds_read_b128 v[92:95], v88 offset:48128
	v_pk_fma_f32 v[4:5], v[2:3], v[50:51], v[4:5] neg_lo:[0,1,0] neg_hi:[0,1,0]
	ds_read_b128 v[84:87], v88 offset:47872
	v_pk_mul_f32 v[8:9], v[44:45], v[16:17] op_sel:[0,1] op_sel_hi:[1,1]
	v_add_f32_e32 v4, v4, v5
	ds_read_b128 v[80:83], v88 offset:47616
	v_pk_mul_f32 v[10:11], v[46:47], v[16:17] op_sel:[0,1] op_sel_hi:[1,1]
	v_add_f32_dpp v4, v4, v4 quad_perm:[1,0,3,2] row_mask:0xf bank_mask:0xf bound_ctrl:1
	ds_read_b128 v[96:99], v88 offset:48384
	v_pk_fma_f32 v[8:9], v[0:1], v[40:41], v[8:9]
	v_add_f32_dpp v4, v4, v4 quad_perm:[2,3,0,1] row_mask:0xf bank_mask:0xf bound_ctrl:1
	v_pk_fma_f32 v[10:11], v[2:3], v[42:43], v[10:11]
	s_nop 0
	v_add_f32_dpp v4, v4, v4 row_ror:4 row_mask:0xf bank_mask:0xf bound_ctrl:1
	ds_read_b128 v[100:103], v88 offset:48640
	s_nop 0
	v_add_f32_dpp v4, v4, v4 row_ror:8 row_mask:0xf bank_mask:0xf bound_ctrl:1
	v_pk_fma_f32 v[0:1], v[4:5], v[52:53], v[8:9] op_sel_hi:[0,1,1]
	v_pk_fma_f32 v[2:3], v[4:5], v[54:55], v[10:11] op_sel_hi:[0,1,1]
	v_pk_mul_f32 v[6:7], v[0:1], v[56:57]
	v_pk_fma_f32 v[6:7], v[2:3], v[58:59], v[6:7]
	v_add_f32_e32 v211, v6, v7
	s_waitcnt lgkmcnt(0)
	s_barrier
	v_pk_mul_f32 v[4:5], v[0:1], v[68:69] neg_lo:[0,1] neg_hi:[0,1]
	ds_read_b128 v[28:31], v88 offset:512
	v_pk_fma_f32 v[4:5], v[2:3], v[70:71], v[4:5] neg_lo:[0,1,0] neg_hi:[0,1,0]
	ds_read_b128 v[24:27], v88 offset:256
	v_pk_mul_f32 v[8:9], v[64:65], v[18:19] op_sel_hi:[1,0]
	v_add_f32_e32 v4, v4, v5
	ds_read_b128 v[20:23], v88 offset:0
	v_pk_mul_f32 v[10:11], v[66:67], v[18:19] op_sel_hi:[1,0]
	v_add_f32_dpp v4, v4, v4 quad_perm:[1,0,3,2] row_mask:0xf bank_mask:0xf bound_ctrl:1
	ds_read_b128 v[32:35], v88 offset:768
	v_pk_fma_f32 v[8:9], v[0:1], v[60:61], v[8:9]
	v_add_f32_dpp v4, v4, v4 quad_perm:[2,3,0,1] row_mask:0xf bank_mask:0xf bound_ctrl:1
	v_pk_fma_f32 v[10:11], v[2:3], v[62:63], v[10:11]
	s_nop 0
	v_add_f32_dpp v4, v4, v4 row_ror:4 row_mask:0xf bank_mask:0xf bound_ctrl:1
	ds_read_b128 v[36:39], v88 offset:1024
	s_nop 0
	v_add_f32_dpp v4, v4, v4 row_ror:8 row_mask:0xf bank_mask:0xf bound_ctrl:1
	v_pk_fma_f32 v[0:1], v[4:5], v[72:73], v[8:9] op_sel_hi:[0,1,1]
	v_pk_fma_f32 v[2:3], v[4:5], v[74:75], v[10:11] op_sel_hi:[0,1,1]
	v_pk_mul_f32 v[6:7], v[0:1], v[76:77]
	v_pk_fma_f32 v[6:7], v[2:3], v[78:79], v[6:7]
	v_add_f32_e32 v212, v6, v7
	ds_read2st64_b32 v[16:17], v90 offset0:5 offset1:11
	s_waitcnt lgkmcnt(6)
	v_pk_mul_f32 v[4:5], v[0:1], v[92:93] neg_lo:[0,1] neg_hi:[0,1]
	ds_read_b128 v[48:51], v88 offset:2048
	v_pk_fma_f32 v[4:5], v[2:3], v[94:95], v[4:5] neg_lo:[0,1,0] neg_hi:[0,1,0]
	ds_read_b128 v[44:47], v88 offset:1792
	v_pk_mul_f32 v[8:9], v[84:85], v[18:19] op_sel:[0,1] op_sel_hi:[1,1]
	v_add_f32_e32 v4, v4, v5
	ds_read_b128 v[40:43], v88 offset:1536
	v_pk_mul_f32 v[10:11], v[86:87], v[18:19] op_sel:[0,1] op_sel_hi:[1,1]
	v_add_f32_dpp v4, v4, v4 quad_perm:[1,0,3,2] row_mask:0xf bank_mask:0xf bound_ctrl:1
	ds_read_b128 v[52:55], v88 offset:2304
	v_pk_fma_f32 v[8:9], v[0:1], v[80:81], v[8:9]
	v_add_f32_dpp v4, v4, v4 quad_perm:[2,3,0,1] row_mask:0xf bank_mask:0xf bound_ctrl:1
	v_pk_fma_f32 v[10:11], v[2:3], v[82:83], v[10:11]
	s_nop 0
	v_add_f32_dpp v4, v4, v4 row_ror:4 row_mask:0xf bank_mask:0xf bound_ctrl:1
	ds_read_b128 v[56:59], v88 offset:2560
	s_nop 0
	v_add_f32_dpp v4, v4, v4 row_ror:8 row_mask:0xf bank_mask:0xf bound_ctrl:1
	v_pk_fma_f32 v[0:1], v[4:5], v[96:97], v[8:9] op_sel_hi:[0,1,1]
	v_pk_fma_f32 v[2:3], v[4:5], v[98:99], v[10:11] op_sel_hi:[0,1,1]
	v_pk_mul_f32 v[6:7], v[0:1], v[100:101]
	v_pk_fma_f32 v[6:7], v[2:3], v[102:103], v[6:7]
	v_add_f32_e32 v213, v6, v7
	s_waitcnt lgkmcnt(5)
	v_pk_mul_f32 v[4:5], v[0:1], v[28:29] neg_lo:[0,1] neg_hi:[0,1]
	ds_read_b128 v[68:71], v88 offset:3584
	v_pk_fma_f32 v[4:5], v[2:3], v[30:31], v[4:5] neg_lo:[0,1,0] neg_hi:[0,1,0]
	ds_read_b128 v[64:67], v88 offset:3328
	v_pk_mul_f32 v[8:9], v[24:25], v[16:17] op_sel_hi:[1,0]
	v_add_f32_e32 v4, v4, v5
	ds_read_b128 v[60:63], v88 offset:3072
	v_pk_mul_f32 v[10:11], v[26:27], v[16:17] op_sel_hi:[1,0]
	v_add_f32_dpp v4, v4, v4 quad_perm:[1,0,3,2] row_mask:0xf bank_mask:0xf bound_ctrl:1
	ds_read_b128 v[72:75], v88 offset:3840
	v_pk_fma_f32 v[8:9], v[0:1], v[20:21], v[8:9]
	v_add_f32_dpp v4, v4, v4 quad_perm:[2,3,0,1] row_mask:0xf bank_mask:0xf bound_ctrl:1
	v_pk_fma_f32 v[10:11], v[2:3], v[22:23], v[10:11]
	s_nop 0
	v_add_f32_dpp v4, v4, v4 row_ror:4 row_mask:0xf bank_mask:0xf bound_ctrl:1
	ds_read_b128 v[76:79], v88 offset:4096
	s_nop 0
	v_add_f32_dpp v4, v4, v4 row_ror:8 row_mask:0xf bank_mask:0xf bound_ctrl:1
	v_pk_fma_f32 v[0:1], v[4:5], v[32:33], v[8:9] op_sel_hi:[0,1,1]
	v_pk_fma_f32 v[2:3], v[4:5], v[34:35], v[10:11] op_sel_hi:[0,1,1]
	v_pk_mul_f32 v[6:7], v[0:1], v[36:37]
	v_pk_fma_f32 v[6:7], v[2:3], v[38:39], v[6:7]
	v_add_f32_e32 v182, v6, v7
	ds_read2st64_b32 v[18:19], v90 offset0:17 offset1:23
	s_cmp_lt_u32 s28, 15
	s_cbranch_scc0 .Lls0_skip2
	global_load_dwordx4 v[120:123], v174, s[12:13]
	global_load_dwordx2 v[158:159], v175, s[14:15]
	global_load_dwordx2 v[160:161], v175, s[16:17]
	global_load_dwordx2 v[162:163], v175, s[18:19]
	global_load_dwordx4 v[124:127], v180, s[20:21]
	global_load_dword v172, v181, s[20:21]
	v_add_u32_e32 v174, s25, v174
	v_add_u32_e32 v175, s26, v175
	v_add_u32_e32 v180, s27, v180
	v_add_u32_e32 v181, s27, v181
.Lls0_back2:
	v_add_f32_dpp v198, v198, v198 row_ror:8 row_mask:0xf bank_mask:0x3 bound_ctrl:1
	v_add_f32_dpp v198, v206, v206 row_ror:8 row_mask:0xf bank_mask:0xc bound_ctrl:1
	v_add_f32_dpp v199, v199, v199 row_ror:8 row_mask:0xf bank_mask:0x3 bound_ctrl:1
	v_add_f32_dpp v199, v207, v207 row_ror:8 row_mask:0xf bank_mask:0xc bound_ctrl:1
	s_waitcnt lgkmcnt(6)
	v_pk_mul_f32 v[4:5], v[0:1], v[48:49] neg_lo:[0,1] neg_hi:[0,1]
	ds_read_b128 v[92:95], v88 offset:5120
	v_pk_fma_f32 v[4:5], v[2:3], v[50:51], v[4:5] neg_lo:[0,1,0] neg_hi:[0,1,0]
	ds_read_b128 v[84:87], v88 offset:4864
	v_pk_mul_f32 v[8:9], v[44:45], v[16:17] op_sel:[0,1] op_sel_hi:[1,1]
	v_add_f32_e32 v4, v4, v5
	ds_read_b128 v[80:83], v88 offset:4608
	v_pk_mul_f32 v[10:11], v[46:47], v[16:17] op_sel:[0,1] op_sel_hi:[1,1]
	v_add_f32_dpp v4, v4, v4 quad_perm:[1,0,3,2] row_mask:0xf bank_mask:0xf bound_ctrl:1
	ds_read_b128 v[96:99], v88 offset:5376
	v_pk_fma_f32 v[8:9], v[0:1], v[40:41], v[8:9]
	v_add_f32_dpp v4, v4, v4 quad_perm:[2,3,0,1] row_mask:0xf bank_mask:0xf bound_ctrl:1
	v_pk_fma_f32 v[10:11], v[2:3], v[42:43], v[10:11]
	s_nop 0
	v_add_f32_dpp v4, v4, v4 row_ror:4 row_mask:0xf bank_mask:0xf bound_ctrl:1
	ds_read_b128 v[100:103], v88 offset:5632
	s_nop 0
	v_add_f32_dpp v4, v4, v4 row_ror:8 row_mask:0xf bank_mask:0xf bound_ctrl:1
	v_pk_fma_f32 v[0:1], v[4:5], v[52:53], v[8:9] op_sel_hi:[0,1,1]
	v_pk_fma_f32 v[2:3], v[4:5], v[54:55], v[10:11] op_sel_hi:[0,1,1]
	v_pk_mul_f32 v[6:7], v[0:1], v[56:57]
	v_pk_fma_f32 v[6:7], v[2:3], v[58:59], v[6:7]
	v_add_f32_e32 v183, v6, v7
	v_add_f32_dpp v200, v200, v200 row_ror:8 row_mask:0xf bank_mask:0x3 bound_ctrl:1
	v_add_f32_dpp v200, v208, v208 row_ror:8 row_mask:0xf bank_mask:0xc bound_ctrl:1
	v_add_f32_dpp v201, v201, v201 row_ror:8 row_mask:0xf bank_mask:0x3 bound_ctrl:1
	v_add_f32_dpp v201, v209, v209 row_ror:8 row_mask:0xf bank_mask:0xc bound_ctrl:1
	s_waitcnt lgkmcnt(5)
	v_pk_mul_f32 v[4:5], v[0:1], v[68:69] neg_lo:[0,1] neg_hi:[0,1]
	ds_read_b128 v[28:31], v88 offset:6656
	v_pk_fma_f32 v[4:5], v[2:3], v[70:71], v[4:5] neg_lo:[0,1,0] neg_hi:[0,1,0]
	ds_read_b128 v[24:27], v88 offset:6400
	v_pk_mul_f32 v[8:9], v[64:65], v[18:19] op_sel_hi:[1,0]
	v_add_f32_e32 v4, v4, v5
	ds_read_b128 v[20:23], v88 offset:6144
	v_pk_mul_f32 v[10:11], v[66:67], v[18:19] op_sel_hi:[1,0]
	v_add_f32_dpp v4, v4, v4 quad_perm:[1,0,3,2] row_mask:0xf bank_mask:0xf bound_ctrl:1
	ds_read_b128 v[32:35], v88 offset:6912
	v_pk_fma_f32 v[8:9], v[0:1], v[60:61], v[8:9]
	v_add_f32_dpp v4, v4, v4 quad_perm:[2,3,0,1] row_mask:0xf bank_mask:0xf bound_ctrl:1
	v_pk_fma_f32 v[10:11], v[2:3], v[62:63], v[10:11]
	s_nop 0
	v_add_f32_dpp v4, v4, v4 row_ror:4 row_mask:0xf bank_mask:0xf bound_ctrl:1
	ds_read_b128 v[36:39], v88 offset:7168
	s_nop 0
	v_add_f32_dpp v4, v4, v4 row_ror:8 row_mask:0xf bank_mask:0xf bound_ctrl:1
	v_pk_fma_f32 v[0:1], v[4:5], v[72:73], v[8:9] op_sel_hi:[0,1,1]
	v_pk_fma_f32 v[2:3], v[4:5], v[74:75], v[10:11] op_sel_hi:[0,1,1]
	v_pk_mul_f32 v[6:7], v[0:1], v[76:77]
	v_pk_fma_f32 v[6:7], v[2:3], v[78:79], v[6:7]
	v_add_f32_e32 v184, v6, v7
	ds_read2st64_b32 v[16:17], v90 offset0:29 offset1:35
	v_add_f32_dpp v202, v202, v202 row_ror:8 row_mask:0xf bank_mask:0x3 bound_ctrl:1
	v_add_f32_dpp v202, v210, v210 row_ror:8 row_mask:0xf bank_mask:0xc bound_ctrl:1
	v_add_f32_dpp v203, v203, v203 row_ror:8 row_mask:0xf bank_mask:0x3 bound_ctrl:1
	v_add_f32_dpp v203, v211, v211 row_ror:8 row_mask:0xf bank_mask:0xc bound_ctrl:1
	s_waitcnt lgkmcnt(6)
	v_pk_mul_f32 v[4:5], v[0:1], v[92:93] neg_lo:[0,1] neg_hi:[0,1]
	ds_read_b128 v[48:51], v88 offset:8192
	v_pk_fma_f32 v[4:5], v[2:3], v[94:95], v[4:5] neg_lo:[0,1,0] neg_hi:[0,1,0]
	ds_read_b128 v[44:47], v88 offset:7936
	v_pk_mul_f32 v[8:9], v[84:85], v[18:19] op_sel:[0,1] op_sel_hi:[1,1]
	v_add_f32_e32 v4, v4, v5
	ds_read_b128 v[40:43], v88 offset:7680
	v_pk_mul_f32 v[10:11], v[86:87], v[18:19] op_sel:[0,1] op_sel_hi:[1,1]
	v_add_f32_dpp v4, v4, v4 quad_perm:[1,0,3,2] row_mask:0xf bank_mask:0xf bound_ctrl:1
	ds_read_b128 v[52:55], v88 offset:8448
	v_pk_fma_f32 v[8:9], v[0:1], v[80:81], v[8:9]
	v_add_f32_dpp v4, v4, v4 quad_perm:[2,3,0,1] row_mask:0xf bank_mask:0xf bound_ctrl:1
	v_pk_fma_f32 v[10:11], v[2:3], v[82:83], v[10:11]
	s_nop 0
	v_add_f32_dpp v4, v4, v4 row_ror:4 row_mask:0xf bank_mask:0xf bound_ctrl:1
	ds_read_b128 v[56:59], v88 offset:8704
	s_nop 0
	v_add_f32_dpp v4, v4, v4 row_ror:8 row_mask:0xf bank_mask:0xf bound_ctrl:1
	v_pk_fma_f32 v[0:1], v[4:5], v[96:97], v[8:9] op_sel_hi:[0,1,1]
	v_pk_fma_f32 v[2:3], v[4:5], v[98:99], v[10:11] op_sel_hi:[0,1,1]
	v_pk_mul_f32 v[6:7], v[0:1], v[100:101]
	v_pk_fma_f32 v[6:7], v[2:3], v[102:103], v[6:7]
	v_add_f32_e32 v185, v6, v7
	v_add_f32_dpp v204, v204, v204 row_ror:8 row_mask:0xf bank_mask:0x3 bound_ctrl:1
	v_add_f32_dpp v204, v212, v212 row_ror:8 row_mask:0xf bank_mask:0xc bound_ctrl:1
	v_add_f32_dpp v205, v205, v205 row_ror:8 row_mask:0xf bank_mask:0x3 bound_ctrl:1
	v_add_f32_dpp v205, v213, v213 row_ror:8 row_mask:0xf bank_mask:0xc bound_ctrl:1
	s_waitcnt lgkmcnt(5)
	v_pk_mul_f32 v[4:5], v[0:1], v[28:29] neg_lo:[0,1] neg_hi:[0,1]
	ds_read_b128 v[68:71], v88 offset:9728
	v_pk_fma_f32 v[4:5], v[2:3], v[30:31], v[4:5] neg_lo:[0,1,0] neg_hi:[0,1,0]
	ds_read_b128 v[64:67], v88 offset:9472
	v_pk_mul_f32 v[8:9], v[24:25], v[16:17] op_sel_hi:[1,0]
	v_add_f32_e32 v4, v4, v5
	ds_read_b128 v[60:63], v88 offset:9216
	v_pk_mul_f32 v[10:11], v[26:27], v[16:17] op_sel_hi:[1,0]
	v_add_f32_dpp v4, v4, v4 quad_perm:[1,0,3,2] row_mask:0xf bank_mask:0xf bound_ctrl:1
	ds_read_b128 v[72:75], v88 offset:9984
	v_pk_fma_f32 v[8:9], v[0:1], v[20:21], v[8:9]
	v_add_f32_dpp v4, v4, v4 quad_perm:[2,3,0,1] row_mask:0xf bank_mask:0xf bound_ctrl:1
	v_pk_fma_f32 v[10:11], v[2:3], v[22:23], v[10:11]
	s_nop 0
	v_add_f32_dpp v4, v4, v4 row_ror:4 row_mask:0xf bank_mask:0xf bound_ctrl:1
	ds_read_b128 v[76:79], v88 offset:10240
	s_nop 0
	v_add_f32_dpp v4, v4, v4 row_ror:8 row_mask:0xf bank_mask:0xf bound_ctrl:1
	v_pk_fma_f32 v[0:1], v[4:5], v[32:33], v[8:9] op_sel_hi:[0,1,1]
	v_pk_fma_f32 v[2:3], v[4:5], v[34:35], v[10:11] op_sel_hi:[0,1,1]
	v_pk_mul_f32 v[6:7], v[0:1], v[36:37]
	v_pk_fma_f32 v[6:7], v[2:3], v[38:39], v[6:7]
	v_add_f32_e32 v186, v6, v7
	ds_read2st64_b32 v[18:19], v90 offset0:41 offset1:47
	v_add_f32_dpp v198, v198, v198 row_shl:4 row_mask:0xf bank_mask:0x5 bound_ctrl:1
	v_add_f32_dpp v198, v202, v202 row_shr:4 row_mask:0xf bank_mask:0xa bound_ctrl:1
	v_add_f32_dpp v199, v199, v199 row_shl:4 row_mask:0xf bank_mask:0x5 bound_ctrl:1
	v_add_f32_dpp v199, v203, v203 row_shr:4 row_mask:0xf bank_mask:0xa bound_ctrl:1
	s_waitcnt vmcnt(19)
	ds_write_b128 v91, v[128:131] offset:24576
	s_waitcnt lgkmcnt(7)
	v_pk_mul_f32 v[4:5], v[0:1], v[48:49] neg_lo:[0,1] neg_hi:[0,1]
	ds_read_b128 v[92:95], v88 offset:11264
	v_pk_fma_f32 v[4:5], v[2:3], v[50:51], v[4:5] neg_lo:[0,1,0] neg_hi:[0,1,0]
	ds_read_b128 v[84:87], v88 offset:11008
	v_pk_mul_f32 v[8:9], v[44:45], v[16:17] op_sel:[0,1] op_sel_hi:[1,1]
	v_add_f32_e32 v4, v4, v5
	ds_read_b128 v[80:83], v88 offset:10752
	v_pk_mul_f32 v[10:11], v[46:47], v[16:17] op_sel:[0,1] op_sel_hi:[1,1]
	v_add_f32_dpp v4, v4, v4 quad_perm:[1,0,3,2] row_mask:0xf bank_mask:0xf bound_ctrl:1
	ds_read_b128 v[96:99], v88 offset:11520
	v_pk_fma_f32 v[8:9], v[0:1], v[40:41], v[8:9]
	v_add_f32_dpp v4, v4, v4 quad_perm:[2,3,0,1] row_mask:0xf bank_mask:0xf bound_ctrl:1
	v_pk_fma_f32 v[10:11], v[2:3], v[42:43], v[10:11]
	s_nop 0
	v_add_f32_dpp v4, v4, v4 row_ror:4 row_mask:0xf bank_mask:0xf bound_ctrl:1
	ds_read_b128 v[100:103], v88 offset:11776
	s_nop 0
	v_add_f32_dpp v4, v4, v4 row_ror:8 row_mask:0xf bank_mask:0xf bound_ctrl:1
	v_pk_fma_f32 v[0:1], v[4:5], v[52:53], v[8:9] op_sel_hi:[0,1,1]
	v_pk_fma_f32 v[2:3], v[4:5], v[54:55], v[10:11] op_sel_hi:[0,1,1]
	v_pk_mul_f32 v[6:7], v[0:1], v[56:57]
	v_pk_fma_f32 v[6:7], v[2:3], v[58:59], v[6:7]
	v_add_f32_e32 v187, v6, v7
	v_add_f32_dpp v200, v200, v200 row_shl:4 row_mask:0xf bank_mask:0x5 bound_ctrl:1
	v_add_f32_dpp v200, v204, v204 row_shr:4 row_mask:0xf bank_mask:0xa bound_ctrl:1
	v_add_f32_dpp v201, v201, v201 row_shl:4 row_mask:0xf bank_mask:0x5 bound_ctrl:1
	v_add_f32_dpp v201, v205, v205 row_shr:4 row_mask:0xf bank_mask:0xa bound_ctrl:1
	ds_write_b128 v91, v[132:135] offset:25600
	ds_write_b32 v91, v173 offset:25856
	s_waitcnt lgkmcnt(8)
	v_pk_mul_f32 v[4:5], v[0:1], v[68:69] neg_lo:[0,1] neg_hi:[0,1]
	ds_read_b128 v[28:31], v88 offset:12800
	v_pk_fma_f32 v[4:5], v[2:3], v[70:71], v[4:5] neg_lo:[0,1,0] neg_hi:[0,1,0]
	ds_read_b128 v[24:27], v88 offset:12544
	v_pk_mul_f32 v[8:9], v[64:65], v[18:19] op_sel_hi:[1,0]
	v_add_f32_e32 v4, v4, v5
	ds_read_b128 v[20:23], v88 offset:12288
	v_pk_mul_f32 v[10:11], v[66:67], v[18:19] op_sel_hi:[1,0]
	v_add_f32_dpp v4, v4, v4 quad_perm:[1,0,3,2] row_mask:0xf bank_mask:0xf bound_ctrl:1
	ds_read_b128 v[32:35], v88 offset:13056
	v_pk_fma_f32 v[8:9], v[0:1], v[60:61], v[8:9]
	v_add_f32_dpp v4, v4, v4 quad_perm:[2,3,0,1] row_mask:0xf bank_mask:0xf bound_ctrl:1
	v_pk_fma_f32 v[10:11], v[2:3], v[62:63], v[10:11]
	s_nop 0
	v_add_f32_dpp v4, v4, v4 row_ror:4 row_mask:0xf bank_mask:0xf bound_ctrl:1
	ds_read_b128 v[36:39], v88 offset:13312
	s_nop 0
	v_add_f32_dpp v4, v4, v4 row_ror:8 row_mask:0xf bank_mask:0xf bound_ctrl:1
	v_pk_fma_f32 v[0:1], v[4:5], v[72:73], v[8:9] op_sel_hi:[0,1,1]
	v_pk_fma_f32 v[2:3], v[4:5], v[74:75], v[10:11] op_sel_hi:[0,1,1]
	v_pk_mul_f32 v[6:7], v[0:1], v[76:77]
	v_pk_fma_f32 v[6:7], v[2:3], v[78:79], v[6:7]
	v_add_f32_e32 v188, v6, v7
	ds_read2st64_b32 v[16:17], v90 offset0:53 offset1:59
	v_add_f32_dpp v198, v198, v198 quad_perm:[1,0,3,2] row_mask:0xf bank_mask:0xf bound_ctrl:1
	v_add_f32_dpp v199, v199, v199 quad_perm:[1,0,3,2] row_mask:0xf bank_mask:0xf bound_ctrl:1
	v_cndmask_b32_e64 v198, v198, v199, s[30:31]
	v_lshlrev_b32_e32 v176, 16, v164
	v_and_b32_e32 v177, 0xffff0000, v164
	s_waitcnt lgkmcnt(8)
	v_pk_mul_f32 v[4:5], v[0:1], v[92:93] neg_lo:[0,1] neg_hi:[0,1]
	ds_read_b128 v[48:51], v88 offset:14336
	v_pk_fma_f32 v[4:5], v[2:3], v[94:95], v[4:5] neg_lo:[0,1,0] neg_hi:[0,1,0]
	ds_read_b128 v[44:47], v88 offset:14080
	v_pk_mul_f32 v[8:9], v[84:85], v[18:19] op_sel:[0,1] op_sel_hi:[1,1]
	v_add_f32_e32 v4, v4, v5
	ds_read_b128 v[40:43], v88 offset:13824
	v_pk_mul_f32 v[10:11], v[86:87], v[18:19] op_sel:[0,1] op_sel_hi:[1,1]
	v_add_f32_dpp v4, v4, v4 quad_perm:[1,0,3,2] row_mask:0xf bank_mask:0xf bound_ctrl:1
	ds_read_b128 v[52:55], v88 offset:14592
	v_pk_fma_f32 v[8:9], v[0:1], v[80:81], v[8:9]
	v_add_f32_dpp v4, v4, v4 quad_perm:[2,3,0,1] row_mask:0xf bank_mask:0xf bound_ctrl:1
	v_pk_fma_f32 v[10:11], v[2:3], v[82:83], v[10:11]
	s_nop 0
	v_add_f32_dpp v4, v4, v4 row_ror:4 row_mask:0xf bank_mask:0xf bound_ctrl:1
	ds_read_b128 v[56:59], v88 offset:14848
	s_nop 0
	v_add_f32_dpp v4, v4, v4 row_ror:8 row_mask:0xf bank_mask:0xf bound_ctrl:1
	v_pk_fma_f32 v[0:1], v[4:5], v[96:97], v[8:9] op_sel_hi:[0,1,1]
	v_pk_fma_f32 v[2:3], v[4:5], v[98:99], v[10:11] op_sel_hi:[0,1,1]
	v_pk_mul_f32 v[6:7], v[0:1], v[100:101]
	v_pk_fma_f32 v[6:7], v[2:3], v[102:103], v[6:7]
	v_add_f32_e32 v189, v6, v7
	v_add_f32_dpp v200, v200, v200 quad_perm:[1,0,3,2] row_mask:0xf bank_mask:0xf bound_ctrl:1
	v_add_f32_dpp v201, v201, v201 quad_perm:[1,0,3,2] row_mask:0xf bank_mask:0xf bound_ctrl:1
	v_cndmask_b32_e64 v200, v200, v201, s[30:31]
	v_lshlrev_b32_e32 v178, 16, v165
	v_and_b32_e32 v179, 0xffff0000, v165
	s_waitcnt lgkmcnt(5)
	v_pk_mul_f32 v[4:5], v[0:1], v[28:29] neg_lo:[0,1] neg_hi:[0,1]
	ds_read_b128 v[68:71], v88 offset:15872
	v_pk_fma_f32 v[4:5], v[2:3], v[30:31], v[4:5] neg_lo:[0,1,0] neg_hi:[0,1,0]
	ds_read_b128 v[64:67], v88 offset:15616
	v_pk_mul_f32 v[8:9], v[24:25], v[16:17] op_sel_hi:[1,0]
	v_add_f32_e32 v4, v4, v5
	ds_read_b128 v[60:63], v88 offset:15360
	v_pk_mul_f32 v[10:11], v[26:27], v[16:17] op_sel_hi:[1,0]
	v_add_f32_dpp v4, v4, v4 quad_perm:[1,0,3,2] row_mask:0xf bank_mask:0xf bound_ctrl:1
	ds_read_b128 v[72:75], v88 offset:16128
	v_pk_fma_f32 v[8:9], v[0:1], v[20:21], v[8:9]
	v_add_f32_dpp v4, v4, v4 quad_perm:[2,3,0,1] row_mask:0xf bank_mask:0xf bound_ctrl:1
	v_pk_fma_f32 v[10:11], v[2:3], v[22:23], v[10:11]
	s_nop 0
	v_add_f32_dpp v4, v4, v4 row_ror:4 row_mask:0xf bank_mask:0xf bound_ctrl:1
	ds_read_b128 v[76:79], v88 offset:16384
	s_nop 0
	v_add_f32_dpp v4, v4, v4 row_ror:8 row_mask:0xf bank_mask:0xf bound_ctrl:1
	v_pk_fma_f32 v[0:1], v[4:5], v[32:33], v[8:9] op_sel_hi:[0,1,1]
	v_pk_fma_f32 v[2:3], v[4:5], v[34:35], v[10:11] op_sel_hi:[0,1,1]
	v_pk_mul_f32 v[6:7], v[0:1], v[36:37]
	v_pk_fma_f32 v[6:7], v[2:3], v[38:39], v[6:7]
	v_add_f32_e32 v190, v6, v7
	ds_read2st64_b32 v[18:19], v90 offset0:65 offset1:71
	v_add_f32_dpp v198, v198, v198 quad_perm:[2,3,0,1] row_mask:0xf bank_mask:0xf bound_ctrl:1
	v_add_f32_dpp v200, v200, v200 quad_perm:[2,3,0,1] row_mask:0xf bank_mask:0xf bound_ctrl:1
	v_cndmask_b32_e64 v214, v198, v200, s[34:35]
	v_cvt_pk_bf16_f32 v214, v214, v214
	ds_write_b128 v91, v[176:179] offset:24832
	v_lshlrev_b32_e32 v176, 16, v166
	s_waitcnt lgkmcnt(7)
	v_pk_mul_f32 v[4:5], v[0:1], v[48:49] neg_lo:[0,1] neg_hi:[0,1]
	ds_read_b128 v[92:95], v88 offset:17408
	v_pk_fma_f32 v[4:5], v[2:3], v[50:51], v[4:5] neg_lo:[0,1,0] neg_hi:[0,1,0]
	ds_read_b128 v[84:87], v88 offset:17152
	v_pk_mul_f32 v[8:9], v[44:45], v[16:17] op_sel:[0,1] op_sel_hi:[1,1]
	v_add_f32_e32 v4, v4, v5
	ds_read_b128 v[80:83], v88 offset:16896
	v_pk_mul_f32 v[10:11], v[46:47], v[16:17] op_sel:[0,1] op_sel_hi:[1,1]
	v_add_f32_dpp v4, v4, v4 quad_perm:[1,0,3,2] row_mask:0xf bank_mask:0xf bound_ctrl:1
	ds_read_b128 v[96:99], v88 offset:17664
	v_pk_fma_f32 v[8:9], v[0:1], v[40:41], v[8:9]
	v_add_f32_dpp v4, v4, v4 quad_perm:[2,3,0,1] row_mask:0xf bank_mask:0xf bound_ctrl:1
	v_pk_fma_f32 v[10:11], v[2:3], v[42:43], v[10:11]
	s_nop 0
	v_add_f32_dpp v4, v4, v4 row_ror:4 row_mask:0xf bank_mask:0xf bound_ctrl:1
	ds_read_b128 v[100:103], v88 offset:17920
	s_nop 0
	v_add_f32_dpp v4, v4, v4 row_ror:8 row_mask:0xf bank_mask:0xf bound_ctrl:1
	v_pk_fma_f32 v[0:1], v[4:5], v[52:53], v[8:9] op_sel_hi:[0,1,1]
	v_pk_fma_f32 v[2:3], v[4:5], v[54:55], v[10:11] op_sel_hi:[0,1,1]
	v_pk_mul_f32 v[6:7], v[0:1], v[56:57]
	v_pk_fma_f32 v[6:7], v[2:3], v[58:59], v[6:7]
	v_add_f32_e32 v191, v6, v7
	global_store_short v145, v214, s[22:23]
	v_add_u32_e32 v145, s26, v145
	v_and_b32_e32 v177, 0xffff0000, v166
	v_lshlrev_b32_e32 v178, 16, v167
	s_waitcnt lgkmcnt(6)
	v_pk_mul_f32 v[4:5], v[0:1], v[68:69] neg_lo:[0,1] neg_hi:[0,1]
	ds_read_b128 v[28:31], v88 offset:18944
	v_pk_fma_f32 v[4:5], v[2:3], v[70:71], v[4:5] neg_lo:[0,1,0] neg_hi:[0,1,0]
	ds_read_b128 v[24:27], v88 offset:18688
	v_pk_mul_f32 v[8:9], v[64:65], v[18:19] op_sel_hi:[1,0]
	v_add_f32_e32 v4, v4, v5
	ds_read_b128 v[20:23], v88 offset:18432
	v_pk_mul_f32 v[10:11], v[66:67], v[18:19] op_sel_hi:[1,0]
	v_add_f32_dpp v4, v4, v4 quad_perm:[1,0,3,2] row_mask:0xf bank_mask:0xf bound_ctrl:1
	ds_read_b128 v[32:35], v88 offset:19200
	v_pk_fma_f32 v[8:9], v[0:1], v[60:61], v[8:9]
	v_add_f32_dpp v4, v4, v4 quad_perm:[2,3,0,1] row_mask:0xf bank_mask:0xf bound_ctrl:1
	v_pk_fma_f32 v[10:11], v[2:3], v[62:63], v[10:11]
	s_nop 0
	v_add_f32_dpp v4, v4, v4 row_ror:4 row_mask:0xf bank_mask:0xf bound_ctrl:1
	ds_read_b128 v[36:39], v88 offset:19456
	s_nop 0
	v_add_f32_dpp v4, v4, v4 row_ror:8 row_mask:0xf bank_mask:0xf bound_ctrl:1
	v_pk_fma_f32 v[0:1], v[4:5], v[72:73], v[8:9] op_sel_hi:[0,1,1]
	v_pk_fma_f32 v[2:3], v[4:5], v[74:75], v[10:11] op_sel_hi:[0,1,1]
	v_pk_mul_f32 v[6:7], v[0:1], v[76:77]
	v_pk_fma_f32 v[6:7], v[2:3], v[78:79], v[6:7]
	v_add_f32_e32 v192, v6, v7
	ds_read2st64_b32 v[16:17], v90 offset0:77 offset1:83
	v_and_b32_e32 v179, 0xffff0000, v167
	ds_write_b128 v91, v[176:179] offset:25088
	s_waitcnt lgkmcnt(7)
	v_pk_mul_f32 v[4:5], v[0:1], v[92:93] neg_lo:[0,1] neg_hi:[0,1]
	ds_read_b128 v[48:51], v88 offset:20480
	v_pk_fma_f32 v[4:5], v[2:3], v[94:95], v[4:5] neg_lo:[0,1,0] neg_hi:[0,1,0]
	ds_read_b128 v[44:47], v88 offset:20224
	v_pk_mul_f32 v[8:9], v[84:85], v[18:19] op_sel:[0,1] op_sel_hi:[1,1]
	v_add_f32_e32 v4, v4, v5
	ds_read_b128 v[40:43], v88 offset:19968
	v_pk_mul_f32 v[10:11], v[86:87], v[18:19] op_sel:[0,1] op_sel_hi:[1,1]
	v_add_f32_dpp v4, v4, v4 quad_perm:[1,0,3,2] row_mask:0xf bank_mask:0xf bound_ctrl:1
	ds_read_b128 v[52:55], v88 offset:20736
	v_pk_fma_f32 v[8:9], v[0:1], v[80:81], v[8:9]
	v_add_f32_dpp v4, v4, v4 quad_perm:[2,3,0,1] row_mask:0xf bank_mask:0xf bound_ctrl:1
	v_pk_fma_f32 v[10:11], v[2:3], v[82:83], v[10:11]
	s_nop 0
	v_add_f32_dpp v4, v4, v4 row_ror:4 row_mask:0xf bank_mask:0xf bound_ctrl:1
	ds_read_b128 v[56:59], v88 offset:20992
	s_nop 0
	v_add_f32_dpp v4, v4, v4 row_ror:8 row_mask:0xf bank_mask:0xf bound_ctrl:1
	v_pk_fma_f32 v[0:1], v[4:5], v[96:97], v[8:9] op_sel_hi:[0,1,1]
	v_pk_fma_f32 v[2:3], v[4:5], v[98:99], v[10:11] op_sel_hi:[0,1,1]
	v_pk_mul_f32 v[6:7], v[0:1], v[100:101]
	v_pk_fma_f32 v[6:7], v[2:3], v[102:103], v[6:7]
	v_add_f32_e32 v193, v6, v7
	v_lshlrev_b32_e32 v176, 16, v168
	v_and_b32_e32 v177, 0xffff0000, v168
	s_waitcnt lgkmcnt(6)
	v_pk_mul_f32 v[4:5], v[0:1], v[28:29] neg_lo:[0,1] neg_hi:[0,1]
	ds_read_b128 v[68:71], v88 offset:22016
	v_pk_fma_f32 v[4:5], v[2:3], v[30:31], v[4:5] neg_lo:[0,1,0] neg_hi:[0,1,0]
	ds_read_b128 v[64:67], v88 offset:21760
	v_pk_mul_f32 v[8:9], v[24:25], v[16:17] op_sel_hi:[1,0]
	v_add_f32_e32 v4, v4, v5
	ds_read_b128 v[60:63], v88 offset:21504
	v_pk_mul_f32 v[10:11], v[26:27], v[16:17] op_sel_hi:[1,0]
	v_add_f32_dpp v4, v4, v4 quad_perm:[1,0,3,2] row_mask:0xf bank_mask:0xf bound_ctrl:1
	ds_read_b128 v[72:75], v88 offset:22272
	v_pk_fma_f32 v[8:9], v[0:1], v[20:21], v[8:9]
	v_add_f32_dpp v4, v4, v4 quad_perm:[2,3,0,1] row_mask:0xf bank_mask:0xf bound_ctrl:1
	v_pk_fma_f32 v[10:11], v[2:3], v[22:23], v[10:11]
	s_nop 0
	v_add_f32_dpp v4, v4, v4 row_ror:4 row_mask:0xf bank_mask:0xf bound_ctrl:1
	ds_read_b128 v[76:79], v88 offset:22528
	s_nop 0
	v_add_f32_dpp v4, v4, v4 row_ror:8 row_mask:0xf bank_mask:0xf bound_ctrl:1
	v_pk_fma_f32 v[0:1], v[4:5], v[32:33], v[8:9] op_sel_hi:[0,1,1]
	v_pk_fma_f32 v[2:3], v[4:5], v[34:35], v[10:11] op_sel_hi:[0,1,1]
	v_pk_mul_f32 v[6:7], v[0:1], v[36:37]
	v_pk_fma_f32 v[6:7], v[2:3], v[38:39], v[6:7]
	v_add_f32_e32 v194, v6, v7
	ds_read2st64_b32 v[18:19], v90 offset0:89 offset1:95
	v_lshlrev_b32_e32 v178, 16, v169
	v_and_b32_e32 v179, 0xffff0000, v169
	ds_write_b128 v91, v[176:179] offset:25344
	s_waitcnt lgkmcnt(7)
	v_pk_mul_f32 v[4:5], v[0:1], v[48:49] neg_lo:[0,1] neg_hi:[0,1]
	ds_read_b128 v[92:95], v88 offset:23552
	v_pk_fma_f32 v[4:5], v[2:3], v[50:51], v[4:5] neg_lo:[0,1,0] neg_hi:[0,1,0]
	ds_read_b128 v[84:87], v88 offset:23296
	v_pk_mul_f32 v[8:9], v[44:45], v[16:17] op_sel:[0,1] op_sel_hi:[1,1]
	v_add_f32_e32 v4, v4, v5
	ds_read_b128 v[80:83], v88 offset:23040
	v_pk_mul_f32 v[10:11], v[46:47], v[16:17] op_sel:[0,1] op_sel_hi:[1,1]
	v_add_f32_dpp v4, v4, v4 quad_perm:[1,0,3,2] row_mask:0xf bank_mask:0xf bound_ctrl:1
	ds_read_b128 v[96:99], v88 offset:23808
	v_pk_fma_f32 v[8:9], v[0:1], v[40:41], v[8:9]
	v_add_f32_dpp v4, v4, v4 quad_perm:[2,3,0,1] row_mask:0xf bank_mask:0xf bound_ctrl:1
	v_pk_fma_f32 v[10:11], v[2:3], v[42:43], v[10:11]
	s_nop 0
	v_add_f32_dpp v4, v4, v4 row_ror:4 row_mask:0xf bank_mask:0xf bound_ctrl:1
	ds_read_b128 v[100:103], v88 offset:24064
	s_nop 0
	v_add_f32_dpp v4, v4, v4 row_ror:8 row_mask:0xf bank_mask:0xf bound_ctrl:1
	v_pk_fma_f32 v[0:1], v[4:5], v[52:53], v[8:9] op_sel_hi:[0,1,1]
	v_pk_fma_f32 v[2:3], v[4:5], v[54:55], v[10:11] op_sel_hi:[0,1,1]
	v_pk_mul_f32 v[6:7], v[0:1], v[56:57]
	v_pk_fma_f32 v[6:7], v[2:3], v[58:59], v[6:7]
	v_add_f32_e32 v195, v6, v7
	s_waitcnt lgkmcnt(0)
	s_barrier
	v_pk_mul_f32 v[4:5], v[0:1], v[68:69] neg_lo:[0,1] neg_hi:[0,1]
	ds_read_b128 v[28:31], v88 offset:25088
	v_pk_fma_f32 v[4:5], v[2:3], v[70:71], v[4:5] neg_lo:[0,1,0] neg_hi:[0,1,0]
	ds_read_b128 v[24:27], v88 offset:24832
	v_pk_mul_f32 v[8:9], v[64:65], v[18:19] op_sel_hi:[1,0]
	v_add_f32_e32 v4, v4, v5
	ds_read_b128 v[20:23], v88 offset:24576
	v_pk_mul_f32 v[10:11], v[66:67], v[18:19] op_sel_hi:[1,0]
	v_add_f32_dpp v4, v4, v4 quad_perm:[1,0,3,2] row_mask:0xf bank_mask:0xf bound_ctrl:1
	ds_read_b128 v[32:35], v88 offset:25344
	v_pk_fma_f32 v[8:9], v[0:1], v[60:61], v[8:9]
	v_add_f32_dpp v4, v4, v4 quad_perm:[2,3,0,1] row_mask:0xf bank_mask:0xf bound_ctrl:1
	v_pk_fma_f32 v[10:11], v[2:3], v[62:63], v[10:11]
	s_nop 0
	v_add_f32_dpp v4, v4, v4 row_ror:4 row_mask:0xf bank_mask:0xf bound_ctrl:1
	ds_read_b128 v[36:39], v88 offset:25600
	s_nop 0
	v_add_f32_dpp v4, v4, v4 row_ror:8 row_mask:0xf bank_mask:0xf bound_ctrl:1
	v_pk_fma_f32 v[0:1], v[4:5], v[72:73], v[8:9] op_sel_hi:[0,1,1]
	v_pk_fma_f32 v[2:3], v[4:5], v[74:75], v[10:11] op_sel_hi:[0,1,1]
	v_pk_mul_f32 v[6:7], v[0:1], v[76:77]
	v_pk_fma_f32 v[6:7], v[2:3], v[78:79], v[6:7]
	v_add_f32_e32 v196, v6, v7
	ds_read2st64_b32 v[16:17], v90 offset0:101 offset1:107
	s_waitcnt lgkmcnt(6)
	v_pk_mul_f32 v[4:5], v[0:1], v[92:93] neg_lo:[0,1] neg_hi:[0,1]
	ds_read_b128 v[48:51], v88 offset:26624
	v_pk_fma_f32 v[4:5], v[2:3], v[94:95], v[4:5] neg_lo:[0,1,0] neg_hi:[0,1,0]
	ds_read_b128 v[44:47], v88 offset:26368
	v_pk_mul_f32 v[8:9], v[84:85], v[18:19] op_sel:[0,1] op_sel_hi:[1,1]
	v_add_f32_e32 v4, v4, v5
	ds_read_b128 v[40:43], v88 offset:26112
	v_pk_mul_f32 v[10:11], v[86:87], v[18:19] op_sel:[0,1] op_sel_hi:[1,1]
	v_add_f32_dpp v4, v4, v4 quad_perm:[1,0,3,2] row_mask:0xf bank_mask:0xf bound_ctrl:1
	ds_read_b128 v[52:55], v88 offset:26880
	v_pk_fma_f32 v[8:9], v[0:1], v[80:81], v[8:9]
	v_add_f32_dpp v4, v4, v4 quad_perm:[2,3,0,1] row_mask:0xf bank_mask:0xf bound_ctrl:1
	v_pk_fma_f32 v[10:11], v[2:3], v[82:83], v[10:11]
	s_nop 0
	v_add_f32_dpp v4, v4, v4 row_ror:4 row_mask:0xf bank_mask:0xf bound_ctrl:1
	ds_read_b128 v[56:59], v88 offset:27136
	s_nop 0
	v_add_f32_dpp v4, v4, v4 row_ror:8 row_mask:0xf bank_mask:0xf bound_ctrl:1
	v_pk_fma_f32 v[0:1], v[4:5], v[96:97], v[8:9] op_sel_hi:[0,1,1]
	v_pk_fma_f32 v[2:3], v[4:5], v[98:99], v[10:11] op_sel_hi:[0,1,1]
	v_pk_mul_f32 v[6:7], v[0:1], v[100:101]
	v_pk_fma_f32 v[6:7], v[2:3], v[102:103], v[6:7]
	v_add_f32_e32 v197, v6, v7
	s_waitcnt lgkmcnt(5)
	v_pk_mul_f32 v[4:5], v[0:1], v[28:29] neg_lo:[0,1] neg_hi:[0,1]
	ds_read_b128 v[68:71], v88 offset:28160
	v_pk_fma_f32 v[4:5], v[2:3], v[30:31], v[4:5] neg_lo:[0,1,0] neg_hi:[0,1,0]
	ds_read_b128 v[64:67], v88 offset:27904
	v_pk_mul_f32 v[8:9], v[24:25], v[16:17] op_sel_hi:[1,0]
	v_add_f32_e32 v4, v4, v5
	ds_read_b128 v[60:63], v88 offset:27648
	v_pk_mul_f32 v[10:11], v[26:27], v[16:17] op_sel_hi:[1,0]
	v_add_f32_dpp v4, v4, v4 quad_perm:[1,0,3,2] row_mask:0xf bank_mask:0xf bound_ctrl:1
	ds_read_b128 v[72:75], v88 offset:28416
	v_pk_fma_f32 v[8:9], v[0:1], v[20:21], v[8:9]
	v_add_f32_dpp v4, v4, v4 quad_perm:[2,3,0,1] row_mask:0xf bank_mask:0xf bound_ctrl:1
	v_pk_fma_f32 v[10:11], v[2:3], v[22:23], v[10:11]
	s_nop 0
	v_add_f32_dpp v4, v4, v4 row_ror:4 row_mask:0xf bank_mask:0xf bound_ctrl:1
	ds_read_b128 v[76:79], v88 offset:28672
	s_nop 0
	v_add_f32_dpp v4, v4, v4 row_ror:8 row_mask:0xf bank_mask:0xf bound_ctrl:1
	v_pk_fma_f32 v[0:1], v[4:5], v[32:33], v[8:9] op_sel_hi:[0,1,1]
	v_pk_fma_f32 v[2:3], v[4:5], v[34:35], v[10:11] op_sel_hi:[0,1,1]
	v_pk_mul_f32 v[6:7], v[0:1], v[36:37]
	v_pk_fma_f32 v[6:7], v[2:3], v[38:39], v[6:7]
	v_add_f32_e32 v198, v6, v7
	ds_read2st64_b32 v[18:19], v90 offset0:113 offset1:119
	s_cmp_lt_u32 s28, 15
	s_cbranch_scc0 .Lls0_skip3
	global_load_dwordx4 v[128:131], v174, s[12:13]
	global_load_dwordx2 v[164:165], v175, s[14:15]
	global_load_dwordx2 v[166:167], v175, s[16:17]
	global_load_dwordx2 v[168:169], v175, s[18:19]
	global_load_dwordx4 v[132:135], v180, s[20:21]
	global_load_dword v173, v181, s[20:21]
	v_add_u32_e32 v174, s25, v174
	v_add_u32_e32 v175, s26, v175
	v_add_u32_e32 v180, s27, v180
	v_add_u32_e32 v181, s27, v181
.Lls0_back3:
	v_add_f32_dpp v182, v182, v182 row_ror:8 row_mask:0xf bank_mask:0x3 bound_ctrl:1
	v_add_f32_dpp v182, v190, v190 row_ror:8 row_mask:0xf bank_mask:0xc bound_ctrl:1
	v_add_f32_dpp v183, v183, v183 row_ror:8 row_mask:0xf bank_mask:0x3 bound_ctrl:1
	v_add_f32_dpp v183, v191, v191 row_ror:8 row_mask:0xf bank_mask:0xc bound_ctrl:1
	s_waitcnt lgkmcnt(6)
	v_pk_mul_f32 v[4:5], v[0:1], v[48:49] neg_lo:[0,1] neg_hi:[0,1]
	ds_read_b128 v[92:95], v88 offset:29696
	v_pk_fma_f32 v[4:5], v[2:3], v[50:51], v[4:5] neg_lo:[0,1,0] neg_hi:[0,1,0]
	ds_read_b128 v[84:87], v88 offset:29440
	v_pk_mul_f32 v[8:9], v[44:45], v[16:17] op_sel:[0,1] op_sel_hi:[1,1]
	v_add_f32_e32 v4, v4, v5
	ds_read_b128 v[80:83], v88 offset:29184
	v_pk_mul_f32 v[10:11], v[46:47], v[16:17] op_sel:[0,1] op_sel_hi:[1,1]
	v_add_f32_dpp v4, v4, v4 quad_perm:[1,0,3,2] row_mask:0xf bank_mask:0xf bound_ctrl:1
	ds_read_b128 v[96:99], v88 offset:29952
	v_pk_fma_f32 v[8:9], v[0:1], v[40:41], v[8:9]
	v_add_f32_dpp v4, v4, v4 quad_perm:[2,3,0,1] row_mask:0xf bank_mask:0xf bound_ctrl:1
	v_pk_fma_f32 v[10:11], v[2:3], v[42:43], v[10:11]
	s_nop 0
	v_add_f32_dpp v4, v4, v4 row_ror:4 row_mask:0xf bank_mask:0xf bound_ctrl:1
	ds_read_b128 v[100:103], v88 offset:30208
	s_nop 0
	v_add_f32_dpp v4, v4, v4 row_ror:8 row_mask:0xf bank_mask:0xf bound_ctrl:1
	v_pk_fma_f32 v[0:1], v[4:5], v[52:53], v[8:9] op_sel_hi:[0,1,1]
	v_pk_fma_f32 v[2:3], v[4:5], v[54:55], v[10:11] op_sel_hi:[0,1,1]
	v_pk_mul_f32 v[6:7], v[0:1], v[56:57]
	v_pk_fma_f32 v[6:7], v[2:3], v[58:59], v[6:7]
	v_add_f32_e32 v199, v6, v7
	v_add_f32_dpp v184, v184, v184 row_ror:8 row_mask:0xf bank_mask:0x3 bound_ctrl:1
	v_add_f32_dpp v184, v192, v192 row_ror:8 row_mask:0xf bank_mask:0xc bound_ctrl:1
	v_add_f32_dpp v185, v185, v185 row_ror:8 row_mask:0xf bank_mask:0x3 bound_ctrl:1
	v_add_f32_dpp v185, v193, v193 row_ror:8 row_mask:0xf bank_mask:0xc bound_ctrl:1
	s_waitcnt lgkmcnt(5)
	v_pk_mul_f32 v[4:5], v[0:1], v[68:69] neg_lo:[0,1] neg_hi:[0,1]
	ds_read_b128 v[28:31], v88 offset:31232
	v_pk_fma_f32 v[4:5], v[2:3], v[70:71], v[4:5] neg_lo:[0,1,0] neg_hi:[0,1,0]
	ds_read_b128 v[24:27], v88 offset:30976
	v_pk_mul_f32 v[8:9], v[64:65], v[18:19] op_sel_hi:[1,0]
	v_add_f32_e32 v4, v4, v5
	ds_read_b128 v[20:23], v88 offset:30720
	v_pk_mul_f32 v[10:11], v[66:67], v[18:19] op_sel_hi:[1,0]
	v_add_f32_dpp v4, v4, v4 quad_perm:[1,0,3,2] row_mask:0xf bank_mask:0xf bound_ctrl:1
	ds_read_b128 v[32:35], v88 offset:31488
	v_pk_fma_f32 v[8:9], v[0:1], v[60:61], v[8:9]
	v_add_f32_dpp v4, v4, v4 quad_perm:[2,3,0,1] row_mask:0xf bank_mask:0xf bound_ctrl:1
	v_pk_fma_f32 v[10:11], v[2:3], v[62:63], v[10:11]
	s_nop 0
	v_add_f32_dpp v4, v4, v4 row_ror:4 row_mask:0xf bank_mask:0xf bound_ctrl:1
	ds_read_b128 v[36:39], v88 offset:31744
	s_nop 0
	v_add_f32_dpp v4, v4, v4 row_ror:8 row_mask:0xf bank_mask:0xf bound_ctrl:1
	v_pk_fma_f32 v[0:1], v[4:5], v[72:73], v[8:9] op_sel_hi:[0,1,1]
	v_pk_fma_f32 v[2:3], v[4:5], v[74:75], v[10:11] op_sel_hi:[0,1,1]
	v_pk_mul_f32 v[6:7], v[0:1], v[76:77]
	v_pk_fma_f32 v[6:7], v[2:3], v[78:79], v[6:7]
	v_add_f32_e32 v200, v6, v7
	ds_read2st64_b32 v[16:17], v90 offset0:125 offset1:131
	v_add_f32_dpp v186, v186, v186 row_ror:8 row_mask:0xf bank_mask:0x3 bound_ctrl:1
	v_add_f32_dpp v186, v194, v194 row_ror:8 row_mask:0xf bank_mask:0xc bound_ctrl:1
	v_add_f32_dpp v187, v187, v187 row_ror:8 row_mask:0xf bank_mask:0x3 bound_ctrl:1
	v_add_f32_dpp v187, v195, v195 row_ror:8 row_mask:0xf bank_mask:0xc bound_ctrl:1
	s_waitcnt lgkmcnt(6)
	v_pk_mul_f32 v[4:5], v[0:1], v[92:93] neg_lo:[0,1] neg_hi:[0,1]
	ds_read_b128 v[48:51], v88 offset:32768
	v_pk_fma_f32 v[4:5], v[2:3], v[94:95], v[4:5] neg_lo:[0,1,0] neg_hi:[0,1,0]
	ds_read_b128 v[44:47], v88 offset:32512
	v_pk_mul_f32 v[8:9], v[84:85], v[18:19] op_sel:[0,1] op_sel_hi:[1,1]
	v_add_f32_e32 v4, v4, v5
	ds_read_b128 v[40:43], v88 offset:32256
	v_pk_mul_f32 v[10:11], v[86:87], v[18:19] op_sel:[0,1] op_sel_hi:[1,1]
	v_add_f32_dpp v4, v4, v4 quad_perm:[1,0,3,2] row_mask:0xf bank_mask:0xf bound_ctrl:1
	ds_read_b128 v[52:55], v88 offset:33024
	v_pk_fma_f32 v[8:9], v[0:1], v[80:81], v[8:9]
	v_add_f32_dpp v4, v4, v4 quad_perm:[2,3,0,1] row_mask:0xf bank_mask:0xf bound_ctrl:1
	v_pk_fma_f32 v[10:11], v[2:3], v[82:83], v[10:11]
	s_nop 0
	v_add_f32_dpp v4, v4, v4 row_ror:4 row_mask:0xf bank_mask:0xf bound_ctrl:1
	ds_read_b128 v[56:59], v88 offset:33280
	s_nop 0
	v_add_f32_dpp v4, v4, v4 row_ror:8 row_mask:0xf bank_mask:0xf bound_ctrl:1
	v_pk_fma_f32 v[0:1], v[4:5], v[96:97], v[8:9] op_sel_hi:[0,1,1]
	v_pk_fma_f32 v[2:3], v[4:5], v[98:99], v[10:11] op_sel_hi:[0,1,1]
	v_pk_mul_f32 v[6:7], v[0:1], v[100:101]
	v_pk_fma_f32 v[6:7], v[2:3], v[102:103], v[6:7]
	v_add_f32_e32 v201, v6, v7
	v_add_f32_dpp v188, v188, v188 row_ror:8 row_mask:0xf bank_mask:0x3 bound_ctrl:1
	v_add_f32_dpp v188, v196, v196 row_ror:8 row_mask:0xf bank_mask:0xc bound_ctrl:1
	v_add_f32_dpp v189, v189, v189 row_ror:8 row_mask:0xf bank_mask:0x3 bound_ctrl:1
	v_add_f32_dpp v189, v197, v197 row_ror:8 row_mask:0xf bank_mask:0xc bound_ctrl:1
	s_waitcnt lgkmcnt(5)
	v_pk_mul_f32 v[4:5], v[0:1], v[28:29] neg_lo:[0,1] neg_hi:[0,1]
	ds_read_b128 v[68:71], v88 offset:34304
	v_pk_fma_f32 v[4:5], v[2:3], v[30:31], v[4:5] neg_lo:[0,1,0] neg_hi:[0,1,0]
	ds_read_b128 v[64:67], v88 offset:34048
	v_pk_mul_f32 v[8:9], v[24:25], v[16:17] op_sel_hi:[1,0]
	v_add_f32_e32 v4, v4, v5
	ds_read_b128 v[60:63], v88 offset:33792
	v_pk_mul_f32 v[10:11], v[26:27], v[16:17] op_sel_hi:[1,0]
	v_add_f32_dpp v4, v4, v4 quad_perm:[1,0,3,2] row_mask:0xf bank_mask:0xf bound_ctrl:1
	ds_read_b128 v[72:75], v88 offset:34560
	v_pk_fma_f32 v[8:9], v[0:1], v[20:21], v[8:9]
	v_add_f32_dpp v4, v4, v4 quad_perm:[2,3,0,1] row_mask:0xf bank_mask:0xf bound_ctrl:1
	v_pk_fma_f32 v[10:11], v[2:3], v[22:23], v[10:11]
	s_nop 0
	v_add_f32_dpp v4, v4, v4 row_ror:4 row_mask:0xf bank_mask:0xf bound_ctrl:1
	ds_read_b128 v[76:79], v88 offset:34816
	s_nop 0
	v_add_f32_dpp v4, v4, v4 row_ror:8 row_mask:0xf bank_mask:0xf bound_ctrl:1
	v_pk_fma_f32 v[0:1], v[4:5], v[32:33], v[8:9] op_sel_hi:[0,1,1]
	v_pk_fma_f32 v[2:3], v[4:5], v[34:35], v[10:11] op_sel_hi:[0,1,1]
	v_pk_mul_f32 v[6:7], v[0:1], v[36:37]
	v_pk_fma_f32 v[6:7], v[2:3], v[38:39], v[6:7]
	v_add_f32_e32 v202, v6, v7
	ds_read2st64_b32 v[18:19], v90 offset0:137 offset1:143
	v_add_f32_dpp v182, v182, v182 row_shl:4 row_mask:0xf bank_mask:0x5 bound_ctrl:1
	v_add_f32_dpp v182, v186, v186 row_shr:4 row_mask:0xf bank_mask:0xa bound_ctrl:1
	v_add_f32_dpp v183, v183, v183 row_shl:4 row_mask:0xf bank_mask:0x5 bound_ctrl:1
	v_add_f32_dpp v183, v187, v187 row_shr:4 row_mask:0xf bank_mask:0xa bound_ctrl:1
	s_waitcnt vmcnt(20)
	ds_write_b128 v91, v[104:107] offset:0
	s_waitcnt lgkmcnt(7)
	v_pk_mul_f32 v[4:5], v[0:1], v[48:49] neg_lo:[0,1] neg_hi:[0,1]
	ds_read_b128 v[92:95], v88 offset:35840
	v_pk_fma_f32 v[4:5], v[2:3], v[50:51], v[4:5] neg_lo:[0,1,0] neg_hi:[0,1,0]
	ds_read_b128 v[84:87], v88 offset:35584
	v_pk_mul_f32 v[8:9], v[44:45], v[16:17] op_sel:[0,1] op_sel_hi:[1,1]
	v_add_f32_e32 v4, v4, v5
	ds_read_b128 v[80:83], v88 offset:35328
	v_pk_mul_f32 v[10:11], v[46:47], v[16:17] op_sel:[0,1] op_sel_hi:[1,1]
	v_add_f32_dpp v4, v4, v4 quad_perm:[1,0,3,2] row_mask:0xf bank_mask:0xf bound_ctrl:1
	ds_read_b128 v[96:99], v88 offset:36096
	v_pk_fma_f32 v[8:9], v[0:1], v[40:41], v[8:9]
	v_add_f32_dpp v4, v4, v4 quad_perm:[2,3,0,1] row_mask:0xf bank_mask:0xf bound_ctrl:1
	v_pk_fma_f32 v[10:11], v[2:3], v[42:43], v[10:11]
	s_nop 0
	v_add_f32_dpp v4, v4, v4 row_ror:4 row_mask:0xf bank_mask:0xf bound_ctrl:1
	ds_read_b128 v[100:103], v88 offset:36352
	s_nop 0
	v_add_f32_dpp v4, v4, v4 row_ror:8 row_mask:0xf bank_mask:0xf bound_ctrl:1
	v_pk_fma_f32 v[0:1], v[4:5], v[52:53], v[8:9] op_sel_hi:[0,1,1]
	v_pk_fma_f32 v[2:3], v[4:5], v[54:55], v[10:11] op_sel_hi:[0,1,1]
	v_pk_mul_f32 v[6:7], v[0:1], v[56:57]
	v_pk_fma_f32 v[6:7], v[2:3], v[58:59], v[6:7]
	v_add_f32_e32 v203, v6, v7
	v_add_f32_dpp v184, v184, v184 row_shl:4 row_mask:0xf bank_mask:0x5 bound_ctrl:1
	v_add_f32_dpp v184, v188, v188 row_shr:4 row_mask:0xf bank_mask:0xa bound_ctrl:1
	v_add_f32_dpp v185, v185, v185 row_shl:4 row_mask:0xf bank_mask:0x5 bound_ctrl:1
	v_add_f32_dpp v185, v189, v189 row_shr:4 row_mask:0xf bank_mask:0xa bound_ctrl:1
	ds_write_b128 v91, v[108:111] offset:1024
	ds_write_b32 v91, v170 offset:1280
	s_waitcnt lgkmcnt(8)
	v_pk_mul_f32 v[4:5], v[0:1], v[68:69] neg_lo:[0,1] neg_hi:[0,1]
	ds_read_b128 v[28:31], v88 offset:37376
	v_pk_fma_f32 v[4:5], v[2:3], v[70:71], v[4:5] neg_lo:[0,1,0] neg_hi:[0,1,0]
	ds_read_b128 v[24:27], v88 offset:37120
	v_pk_mul_f32 v[8:9], v[64:65], v[18:19] op_sel_hi:[1,0]
	v_add_f32_e32 v4, v4, v5
	ds_read_b128 v[20:23], v88 offset:36864
	v_pk_mul_f32 v[10:11], v[66:67], v[18:19] op_sel_hi:[1,0]
	v_add_f32_dpp v4, v4, v4 quad_perm:[1,0,3,2] row_mask:0xf bank_mask:0xf bound_ctrl:1
	ds_read_b128 v[32:35], v88 offset:37632
	v_pk_fma_f32 v[8:9], v[0:1], v[60:61], v[8:9]
	v_add_f32_dpp v4, v4, v4 quad_perm:[2,3,0,1] row_mask:0xf bank_mask:0xf bound_ctrl:1
	v_pk_fma_f32 v[10:11], v[2:3], v[62:63], v[10:11]
	s_nop 0
	v_add_f32_dpp v4, v4, v4 row_ror:4 row_mask:0xf bank_mask:0xf bound_ctrl:1
	ds_read_b128 v[36:39], v88 offset:37888
	s_nop 0
	v_add_f32_dpp v4, v4, v4 row_ror:8 row_mask:0xf bank_mask:0xf bound_ctrl:1
	v_pk_fma_f32 v[0:1], v[4:5], v[72:73], v[8:9] op_sel_hi:[0,1,1]
	v_pk_fma_f32 v[2:3], v[4:5], v[74:75], v[10:11] op_sel_hi:[0,1,1]
	v_pk_mul_f32 v[6:7], v[0:1], v[76:77]
	v_pk_fma_f32 v[6:7], v[2:3], v[78:79], v[6:7]
	v_add_f32_e32 v204, v6, v7
	ds_read2st64_b32 v[16:17], v90 offset0:149 offset1:155
	v_add_f32_dpp v182, v182, v182 quad_perm:[1,0,3,2] row_mask:0xf bank_mask:0xf bound_ctrl:1
	v_add_f32_dpp v183, v183, v183 quad_perm:[1,0,3,2] row_mask:0xf bank_mask:0xf bound_ctrl:1
	v_cndmask_b32_e64 v182, v182, v183, s[30:31]
	v_lshlrev_b32_e32 v176, 16, v146
	v_and_b32_e32 v177, 0xffff0000, v146
	s_waitcnt lgkmcnt(8)
	v_pk_mul_f32 v[4:5], v[0:1], v[92:93] neg_lo:[0,1] neg_hi:[0,1]
	ds_read_b128 v[48:51], v88 offset:38912
	v_pk_fma_f32 v[4:5], v[2:3], v[94:95], v[4:5] neg_lo:[0,1,0] neg_hi:[0,1,0]
	ds_read_b128 v[44:47], v88 offset:38656
	v_pk_mul_f32 v[8:9], v[84:85], v[18:19] op_sel:[0,1] op_sel_hi:[1,1]
	v_add_f32_e32 v4, v4, v5
	ds_read_b128 v[40:43], v88 offset:38400
	v_pk_mul_f32 v[10:11], v[86:87], v[18:19] op_sel:[0,1] op_sel_hi:[1,1]
	v_add_f32_dpp v4, v4, v4 quad_perm:[1,0,3,2] row_mask:0xf bank_mask:0xf bound_ctrl:1
	ds_read_b128 v[52:55], v88 offset:39168
	v_pk_fma_f32 v[8:9], v[0:1], v[80:81], v[8:9]
	v_add_f32_dpp v4, v4, v4 quad_perm:[2,3,0,1] row_mask:0xf bank_mask:0xf bound_ctrl:1
	v_pk_fma_f32 v[10:11], v[2:3], v[82:83], v[10:11]
	s_nop 0
	v_add_f32_dpp v4, v4, v4 row_ror:4 row_mask:0xf bank_mask:0xf bound_ctrl:1
	ds_read_b128 v[56:59], v88 offset:39424
	s_nop 0
	v_add_f32_dpp v4, v4, v4 row_ror:8 row_mask:0xf bank_mask:0xf bound_ctrl:1
	v_pk_fma_f32 v[0:1], v[4:5], v[96:97], v[8:9] op_sel_hi:[0,1,1]
	v_pk_fma_f32 v[2:3], v[4:5], v[98:99], v[10:11] op_sel_hi:[0,1,1]
	v_pk_mul_f32 v[6:7], v[0:1], v[100:101]
	v_pk_fma_f32 v[6:7], v[2:3], v[102:103], v[6:7]
	v_add_f32_e32 v205, v6, v7
	v_add_f32_dpp v184, v184, v184 quad_perm:[1,0,3,2] row_mask:0xf bank_mask:0xf bound_ctrl:1
	v_add_f32_dpp v185, v185, v185 quad_perm:[1,0,3,2] row_mask:0xf bank_mask:0xf bound_ctrl:1
	v_cndmask_b32_e64 v184, v184, v185, s[30:31]
	v_lshlrev_b32_e32 v178, 16, v147
	v_and_b32_e32 v179, 0xffff0000, v147
	s_waitcnt lgkmcnt(5)
	v_pk_mul_f32 v[4:5], v[0:1], v[28:29] neg_lo:[0,1] neg_hi:[0,1]
	ds_read_b128 v[68:71], v88 offset:40448
	v_pk_fma_f32 v[4:5], v[2:3], v[30:31], v[4:5] neg_lo:[0,1,0] neg_hi:[0,1,0]
	ds_read_b128 v[64:67], v88 offset:40192
	v_pk_mul_f32 v[8:9], v[24:25], v[16:17] op_sel_hi:[1,0]
	v_add_f32_e32 v4, v4, v5
	ds_read_b128 v[60:63], v88 offset:39936
	v_pk_mul_f32 v[10:11], v[26:27], v[16:17] op_sel_hi:[1,0]
	v_add_f32_dpp v4, v4, v4 quad_perm:[1,0,3,2] row_mask:0xf bank_mask:0xf bound_ctrl:1
	ds_read_b128 v[72:75], v88 offset:40704
	v_pk_fma_f32 v[8:9], v[0:1], v[20:21], v[8:9]
	v_add_f32_dpp v4, v4, v4 quad_perm:[2,3,0,1] row_mask:0xf bank_mask:0xf bound_ctrl:1
	v_pk_fma_f32 v[10:11], v[2:3], v[22:23], v[10:11]
	s_nop 0
	v_add_f32_dpp v4, v4, v4 row_ror:4 row_mask:0xf bank_mask:0xf bound_ctrl:1
	ds_read_b128 v[76:79], v88 offset:40960
	s_nop 0
	v_add_f32_dpp v4, v4, v4 row_ror:8 row_mask:0xf bank_mask:0xf bound_ctrl:1
	v_pk_fma_f32 v[0:1], v[4:5], v[32:33], v[8:9] op_sel_hi:[0,1,1]
	v_pk_fma_f32 v[2:3], v[4:5], v[34:35], v[10:11] op_sel_hi:[0,1,1]
	v_pk_mul_f32 v[6:7], v[0:1], v[36:37]
	v_pk_fma_f32 v[6:7], v[2:3], v[38:39], v[6:7]
	v_add_f32_e32 v206, v6, v7
	ds_read2st64_b32 v[18:19], v90 offset0:161 offset1:167
	v_add_f32_dpp v182, v182, v182 quad_perm:[2,3,0,1] row_mask:0xf bank_mask:0xf bound_ctrl:1
	v_add_f32_dpp v184, v184, v184 quad_perm:[2,3,0,1] row_mask:0xf bank_mask:0xf bound_ctrl:1
	v_cndmask_b32_e64 v214, v182, v184, s[34:35]
	v_cvt_pk_bf16_f32 v214, v214, v214
	ds_write_b128 v91, v[176:179] offset:256
	v_lshlrev_b32_e32 v176, 16, v148
	s_waitcnt lgkmcnt(7)
	v_pk_mul_f32 v[4:5], v[0:1], v[48:49] neg_lo:[0,1] neg_hi:[0,1]
	ds_read_b128 v[92:95], v88 offset:41984
	v_pk_fma_f32 v[4:5], v[2:3], v[50:51], v[4:5] neg_lo:[0,1,0] neg_hi:[0,1,0]
	ds_read_b128 v[84:87], v88 offset:41728
	v_pk_mul_f32 v[8:9], v[44:45], v[16:17] op_sel:[0,1] op_sel_hi:[1,1]
	v_add_f32_e32 v4, v4, v5
	ds_read_b128 v[80:83], v88 offset:41472
	v_pk_mul_f32 v[10:11], v[46:47], v[16:17] op_sel:[0,1] op_sel_hi:[1,1]
	v_add_f32_dpp v4, v4, v4 quad_perm:[1,0,3,2] row_mask:0xf bank_mask:0xf bound_ctrl:1
	ds_read_b128 v[96:99], v88 offset:42240
	v_pk_fma_f32 v[8:9], v[0:1], v[40:41], v[8:9]
	v_add_f32_dpp v4, v4, v4 quad_perm:[2,3,0,1] row_mask:0xf bank_mask:0xf bound_ctrl:1
	v_pk_fma_f32 v[10:11], v[2:3], v[42:43], v[10:11]
	s_nop 0
	v_add_f32_dpp v4, v4, v4 row_ror:4 row_mask:0xf bank_mask:0xf bound_ctrl:1
	ds_read_b128 v[100:103], v88 offset:42496
	s_nop 0
	v_add_f32_dpp v4, v4, v4 row_ror:8 row_mask:0xf bank_mask:0xf bound_ctrl:1
	v_pk_fma_f32 v[0:1], v[4:5], v[52:53], v[8:9] op_sel_hi:[0,1,1]
	v_pk_fma_f32 v[2:3], v[4:5], v[54:55], v[10:11] op_sel_hi:[0,1,1]
	v_pk_mul_f32 v[6:7], v[0:1], v[56:57]
	v_pk_fma_f32 v[6:7], v[2:3], v[58:59], v[6:7]
	v_add_f32_e32 v207, v6, v7
	global_store_short v145, v214, s[22:23]
	v_add_u32_e32 v145, s26, v145
	v_and_b32_e32 v177, 0xffff0000, v148
	v_lshlrev_b32_e32 v178, 16, v149
	s_waitcnt lgkmcnt(6)
	v_pk_mul_f32 v[4:5], v[0:1], v[68:69] neg_lo:[0,1] neg_hi:[0,1]
	ds_read_b128 v[28:31], v88 offset:43520
	v_pk_fma_f32 v[4:5], v[2:3], v[70:71], v[4:5] neg_lo:[0,1,0] neg_hi:[0,1,0]
	ds_read_b128 v[24:27], v88 offset:43264
	v_pk_mul_f32 v[8:9], v[64:65], v[18:19] op_sel_hi:[1,0]
	v_add_f32_e32 v4, v4, v5
	ds_read_b128 v[20:23], v88 offset:43008
	v_pk_mul_f32 v[10:11], v[66:67], v[18:19] op_sel_hi:[1,0]
	v_add_f32_dpp v4, v4, v4 quad_perm:[1,0,3,2] row_mask:0xf bank_mask:0xf bound_ctrl:1
	ds_read_b128 v[32:35], v88 offset:43776
	v_pk_fma_f32 v[8:9], v[0:1], v[60:61], v[8:9]
	v_add_f32_dpp v4, v4, v4 quad_perm:[2,3,0,1] row_mask:0xf bank_mask:0xf bound_ctrl:1
	v_pk_fma_f32 v[10:11], v[2:3], v[62:63], v[10:11]
	s_nop 0
	v_add_f32_dpp v4, v4, v4 row_ror:4 row_mask:0xf bank_mask:0xf bound_ctrl:1
	ds_read_b128 v[36:39], v88 offset:44032
	s_nop 0
	v_add_f32_dpp v4, v4, v4 row_ror:8 row_mask:0xf bank_mask:0xf bound_ctrl:1
	v_pk_fma_f32 v[0:1], v[4:5], v[72:73], v[8:9] op_sel_hi:[0,1,1]
	v_pk_fma_f32 v[2:3], v[4:5], v[74:75], v[10:11] op_sel_hi:[0,1,1]
	v_pk_mul_f32 v[6:7], v[0:1], v[76:77]
	v_pk_fma_f32 v[6:7], v[2:3], v[78:79], v[6:7]
	v_add_f32_e32 v208, v6, v7
	ds_read2st64_b32 v[16:17], v90 offset0:173 offset1:179
	v_and_b32_e32 v179, 0xffff0000, v149
	ds_write_b128 v91, v[176:179] offset:512
	s_waitcnt lgkmcnt(7)
	v_pk_mul_f32 v[4:5], v[0:1], v[92:93] neg_lo:[0,1] neg_hi:[0,1]
	ds_read_b128 v[48:51], v88 offset:45056
	v_pk_fma_f32 v[4:5], v[2:3], v[94:95], v[4:5] neg_lo:[0,1,0] neg_hi:[0,1,0]
	ds_read_b128 v[44:47], v88 offset:44800
	v_pk_mul_f32 v[8:9], v[84:85], v[18:19] op_sel:[0,1] op_sel_hi:[1,1]
	v_add_f32_e32 v4, v4, v5
	ds_read_b128 v[40:43], v88 offset:44544
	v_pk_mul_f32 v[10:11], v[86:87], v[18:19] op_sel:[0,1] op_sel_hi:[1,1]
	v_add_f32_dpp v4, v4, v4 quad_perm:[1,0,3,2] row_mask:0xf bank_mask:0xf bound_ctrl:1
	ds_read_b128 v[52:55], v88 offset:45312
	v_pk_fma_f32 v[8:9], v[0:1], v[80:81], v[8:9]
	v_add_f32_dpp v4, v4, v4 quad_perm:[2,3,0,1] row_mask:0xf bank_mask:0xf bound_ctrl:1
	v_pk_fma_f32 v[10:11], v[2:3], v[82:83], v[10:11]
	s_nop 0
	v_add_f32_dpp v4, v4, v4 row_ror:4 row_mask:0xf bank_mask:0xf bound_ctrl:1
	ds_read_b128 v[56:59], v88 offset:45568
	s_nop 0
	v_add_f32_dpp v4, v4, v4 row_ror:8 row_mask:0xf bank_mask:0xf bound_ctrl:1
	v_pk_fma_f32 v[0:1], v[4:5], v[96:97], v[8:9] op_sel_hi:[0,1,1]
	v_pk_fma_f32 v[2:3], v[4:5], v[98:99], v[10:11] op_sel_hi:[0,1,1]
	v_pk_mul_f32 v[6:7], v[0:1], v[100:101]
	v_pk_fma_f32 v[6:7], v[2:3], v[102:103], v[6:7]
	v_add_f32_e32 v209, v6, v7
	v_lshlrev_b32_e32 v176, 16, v150
	v_and_b32_e32 v177, 0xffff0000, v150
	s_waitcnt lgkmcnt(6)
	v_pk_mul_f32 v[4:5], v[0:1], v[28:29] neg_lo:[0,1] neg_hi:[0,1]
	ds_read_b128 v[68:71], v88 offset:46592
	v_pk_fma_f32 v[4:5], v[2:3], v[30:31], v[4:5] neg_lo:[0,1,0] neg_hi:[0,1,0]
	ds_read_b128 v[64:67], v88 offset:46336
	v_pk_mul_f32 v[8:9], v[24:25], v[16:17] op_sel_hi:[1,0]
	v_add_f32_e32 v4, v4, v5
	ds_read_b128 v[60:63], v88 offset:46080
	v_pk_mul_f32 v[10:11], v[26:27], v[16:17] op_sel_hi:[1,0]
	v_add_f32_dpp v4, v4, v4 quad_perm:[1,0,3,2] row_mask:0xf bank_mask:0xf bound_ctrl:1
	ds_read_b128 v[72:75], v88 offset:46848
	v_pk_fma_f32 v[8:9], v[0:1], v[20:21], v[8:9]
	v_add_f32_dpp v4, v4, v4 quad_perm:[2,3,0,1] row_mask:0xf bank_mask:0xf bound_ctrl:1
	v_pk_fma_f32 v[10:11], v[2:3], v[22:23], v[10:11]
	s_nop 0
	v_add_f32_dpp v4, v4, v4 row_ror:4 row_mask:0xf bank_mask:0xf bound_ctrl:1
	ds_read_b128 v[76:79], v88 offset:47104
	s_nop 0
	v_add_f32_dpp v4, v4, v4 row_ror:8 row_mask:0xf bank_mask:0xf bound_ctrl:1
	v_pk_fma_f32 v[0:1], v[4:5], v[32:33], v[8:9] op_sel_hi:[0,1,1]
	v_pk_fma_f32 v[2:3], v[4:5], v[34:35], v[10:11] op_sel_hi:[0,1,1]
	v_pk_mul_f32 v[6:7], v[0:1], v[36:37]
	v_pk_fma_f32 v[6:7], v[2:3], v[38:39], v[6:7]
	v_add_f32_e32 v210, v6, v7
	ds_read2st64_b32 v[18:19], v90 offset0:185 offset1:191
	v_lshlrev_b32_e32 v178, 16, v151
	v_and_b32_e32 v179, 0xffff0000, v151
	ds_write_b128 v91, v[176:179] offset:768
	s_waitcnt lgkmcnt(7)
	v_pk_mul_f32 v[4:5], v[0:1], v[48:49] neg_lo:[0,1] neg_hi:[0,1]
	ds_read_b128 v[92:95], v88 offset:48128
	v_pk_fma_f32 v[4:5], v[2:3], v[50:51], v[4:5] neg_lo:[0,1,0] neg_hi:[0,1,0]
	ds_read_b128 v[84:87], v88 offset:47872
	v_pk_mul_f32 v[8:9], v[44:45], v[16:17] op_sel:[0,1] op_sel_hi:[1,1]
	v_add_f32_e32 v4, v4, v5
	ds_read_b128 v[80:83], v88 offset:47616
	v_pk_mul_f32 v[10:11], v[46:47], v[16:17] op_sel:[0,1] op_sel_hi:[1,1]
	v_add_f32_dpp v4, v4, v4 quad_perm:[1,0,3,2] row_mask:0xf bank_mask:0xf bound_ctrl:1
	ds_read_b128 v[96:99], v88 offset:48384
	v_pk_fma_f32 v[8:9], v[0:1], v[40:41], v[8:9]
	v_add_f32_dpp v4, v4, v4 quad_perm:[2,3,0,1] row_mask:0xf bank_mask:0xf bound_ctrl:1
	v_pk_fma_f32 v[10:11], v[2:3], v[42:43], v[10:11]
	s_nop 0
	v_add_f32_dpp v4, v4, v4 row_ror:4 row_mask:0xf bank_mask:0xf bound_ctrl:1
	ds_read_b128 v[100:103], v88 offset:48640
	s_nop 0
	v_add_f32_dpp v4, v4, v4 row_ror:8 row_mask:0xf bank_mask:0xf bound_ctrl:1
	v_pk_fma_f32 v[0:1], v[4:5], v[52:53], v[8:9] op_sel_hi:[0,1,1]
	v_pk_fma_f32 v[2:3], v[4:5], v[54:55], v[10:11] op_sel_hi:[0,1,1]
	v_pk_mul_f32 v[6:7], v[0:1], v[56:57]
	v_pk_fma_f32 v[6:7], v[2:3], v[58:59], v[6:7]
	v_add_f32_e32 v211, v6, v7
	s_waitcnt lgkmcnt(0)
	s_barrier
	v_pk_mul_f32 v[4:5], v[0:1], v[68:69] neg_lo:[0,1] neg_hi:[0,1]
	ds_read_b128 v[28:31], v88 offset:512
	v_pk_fma_f32 v[4:5], v[2:3], v[70:71], v[4:5] neg_lo:[0,1,0] neg_hi:[0,1,0]
	ds_read_b128 v[24:27], v88 offset:256
	v_pk_mul_f32 v[8:9], v[64:65], v[18:19] op_sel_hi:[1,0]
	v_add_f32_e32 v4, v4, v5
	ds_read_b128 v[20:23], v88 offset:0
	v_pk_mul_f32 v[10:11], v[66:67], v[18:19] op_sel_hi:[1,0]
	v_add_f32_dpp v4, v4, v4 quad_perm:[1,0,3,2] row_mask:0xf bank_mask:0xf bound_ctrl:1
	ds_read_b128 v[32:35], v88 offset:768
	v_pk_fma_f32 v[8:9], v[0:1], v[60:61], v[8:9]
	v_add_f32_dpp v4, v4, v4 quad_perm:[2,3,0,1] row_mask:0xf bank_mask:0xf bound_ctrl:1
	v_pk_fma_f32 v[10:11], v[2:3], v[62:63], v[10:11]
	s_nop 0
	v_add_f32_dpp v4, v4, v4 row_ror:4 row_mask:0xf bank_mask:0xf bound_ctrl:1
	ds_read_b128 v[36:39], v88 offset:1024
	s_nop 0
	v_add_f32_dpp v4, v4, v4 row_ror:8 row_mask:0xf bank_mask:0xf bound_ctrl:1
	v_pk_fma_f32 v[0:1], v[4:5], v[72:73], v[8:9] op_sel_hi:[0,1,1]
	v_pk_fma_f32 v[2:3], v[4:5], v[74:75], v[10:11] op_sel_hi:[0,1,1]
	v_pk_mul_f32 v[6:7], v[0:1], v[76:77]
	v_pk_fma_f32 v[6:7], v[2:3], v[78:79], v[6:7]
	v_add_f32_e32 v212, v6, v7
	ds_read2st64_b32 v[16:17], v90 offset0:5 offset1:11
	s_waitcnt lgkmcnt(6)
	v_pk_mul_f32 v[4:5], v[0:1], v[92:93] neg_lo:[0,1] neg_hi:[0,1]
	ds_read_b128 v[48:51], v88 offset:2048
	v_pk_fma_f32 v[4:5], v[2:3], v[94:95], v[4:5] neg_lo:[0,1,0] neg_hi:[0,1,0]
	ds_read_b128 v[44:47], v88 offset:1792
	v_pk_mul_f32 v[8:9], v[84:85], v[18:19] op_sel:[0,1] op_sel_hi:[1,1]
	v_add_f32_e32 v4, v4, v5
	ds_read_b128 v[40:43], v88 offset:1536
	v_pk_mul_f32 v[10:11], v[86:87], v[18:19] op_sel:[0,1] op_sel_hi:[1,1]
	v_add_f32_dpp v4, v4, v4 quad_perm:[1,0,3,2] row_mask:0xf bank_mask:0xf bound_ctrl:1
	ds_read_b128 v[52:55], v88 offset:2304
	v_pk_fma_f32 v[8:9], v[0:1], v[80:81], v[8:9]
	v_add_f32_dpp v4, v4, v4 quad_perm:[2,3,0,1] row_mask:0xf bank_mask:0xf bound_ctrl:1
	v_pk_fma_f32 v[10:11], v[2:3], v[82:83], v[10:11]
	s_nop 0
	v_add_f32_dpp v4, v4, v4 row_ror:4 row_mask:0xf bank_mask:0xf bound_ctrl:1
	ds_read_b128 v[56:59], v88 offset:2560
	s_nop 0
	v_add_f32_dpp v4, v4, v4 row_ror:8 row_mask:0xf bank_mask:0xf bound_ctrl:1
	v_pk_fma_f32 v[0:1], v[4:5], v[96:97], v[8:9] op_sel_hi:[0,1,1]
	v_pk_fma_f32 v[2:3], v[4:5], v[98:99], v[10:11] op_sel_hi:[0,1,1]
	v_pk_mul_f32 v[6:7], v[0:1], v[100:101]
	v_pk_fma_f32 v[6:7], v[2:3], v[102:103], v[6:7]
	v_add_f32_e32 v213, v6, v7
	s_add_i32 s28, s28, 1
	s_cmp_lt_u32 s28, 16
	s_cbranch_scc1 .Lls0_loop
	s_nop 1
	s_nop 1
	v_add_f32_dpp v198, v198, v198 row_ror:8 row_mask:0xf bank_mask:0x3 bound_ctrl:1
	s_nop 1
	v_add_f32_dpp v198, v206, v206 row_ror:8 row_mask:0xf bank_mask:0xc bound_ctrl:1
	s_nop 1
	v_add_f32_dpp v199, v199, v199 row_ror:8 row_mask:0xf bank_mask:0x3 bound_ctrl:1
	s_nop 1
	v_add_f32_dpp v199, v207, v207 row_ror:8 row_mask:0xf bank_mask:0xc bound_ctrl:1
	s_nop 1
	v_add_f32_dpp v200, v200, v200 row_ror:8 row_mask:0xf bank_mask:0x3 bound_ctrl:1
	s_nop 1
	v_add_f32_dpp v200, v208, v208 row_ror:8 row_mask:0xf bank_mask:0xc bound_ctrl:1
	s_nop 1
	v_add_f32_dpp v201, v201, v201 row_ror:8 row_mask:0xf bank_mask:0x3 bound_ctrl:1
	s_nop 1
	v_add_f32_dpp v201, v209, v209 row_ror:8 row_mask:0xf bank_mask:0xc bound_ctrl:1
	s_nop 1
	v_add_f32_dpp v202, v202, v202 row_ror:8 row_mask:0xf bank_mask:0x3 bound_ctrl:1
	s_nop 1
	v_add_f32_dpp v202, v210, v210 row_ror:8 row_mask:0xf bank_mask:0xc bound_ctrl:1
	s_nop 1
	v_add_f32_dpp v203, v203, v203 row_ror:8 row_mask:0xf bank_mask:0x3 bound_ctrl:1
	s_nop 1
	v_add_f32_dpp v203, v211, v211 row_ror:8 row_mask:0xf bank_mask:0xc bound_ctrl:1
	s_nop 1
	v_add_f32_dpp v204, v204, v204 row_ror:8 row_mask:0xf bank_mask:0x3 bound_ctrl:1
	s_nop 1
	v_add_f32_dpp v204, v212, v212 row_ror:8 row_mask:0xf bank_mask:0xc bound_ctrl:1
	s_nop 1
	v_add_f32_dpp v205, v205, v205 row_ror:8 row_mask:0xf bank_mask:0x3 bound_ctrl:1
	s_nop 1
	v_add_f32_dpp v205, v213, v213 row_ror:8 row_mask:0xf bank_mask:0xc bound_ctrl:1
	s_nop 1
	v_add_f32_dpp v198, v198, v198 row_shl:4 row_mask:0xf bank_mask:0x5 bound_ctrl:1
	s_nop 1
	v_add_f32_dpp v198, v202, v202 row_shr:4 row_mask:0xf bank_mask:0xa bound_ctrl:1
	s_nop 1
	v_add_f32_dpp v199, v199, v199 row_shl:4 row_mask:0xf bank_mask:0x5 bound_ctrl:1
	s_nop 1
	v_add_f32_dpp v199, v203, v203 row_shr:4 row_mask:0xf bank_mask:0xa bound_ctrl:1
	s_nop 1
	v_add_f32_dpp v200, v200, v200 row_shl:4 row_mask:0xf bank_mask:0x5 bound_ctrl:1
	s_nop 1
	v_add_f32_dpp v200, v204, v204 row_shr:4 row_mask:0xf bank_mask:0xa bound_ctrl:1
	s_nop 1
	v_add_f32_dpp v201, v201, v201 row_shl:4 row_mask:0xf bank_mask:0x5 bound_ctrl:1
	s_nop 1
	v_add_f32_dpp v201, v205, v205 row_shr:4 row_mask:0xf bank_mask:0xa bound_ctrl:1
	s_nop 1
	v_add_f32_dpp v198, v198, v198 quad_perm:[1,0,3,2] row_mask:0xf bank_mask:0xf bound_ctrl:1
	s_nop 1
	v_add_f32_dpp v199, v199, v199 quad_perm:[1,0,3,2] row_mask:0xf bank_mask:0xf bound_ctrl:1
	v_cndmask_b32_e64 v198, v198, v199, s[30:31]
	s_nop 1
	v_add_f32_dpp v200, v200, v200 quad_perm:[1,0,3,2] row_mask:0xf bank_mask:0xf bound_ctrl:1
	s_nop 1
	v_add_f32_dpp v201, v201, v201 quad_perm:[1,0,3,2] row_mask:0xf bank_mask:0xf bound_ctrl:1
	v_cndmask_b32_e64 v200, v200, v201, s[30:31]
	s_nop 1
	v_add_f32_dpp v198, v198, v198 quad_perm:[2,3,0,1] row_mask:0xf bank_mask:0xf bound_ctrl:1
	s_nop 1
	v_add_f32_dpp v200, v200, v200 quad_perm:[2,3,0,1] row_mask:0xf bank_mask:0xf bound_ctrl:1
	v_cndmask_b32_e64 v214, v198, v200, s[34:35]
	v_cvt_pk_bf16_f32 v214, v214, v214
	global_store_short v145, v214, s[22:23]
	s_waitcnt lgkmcnt(0)
	s_branch .LBB0_906

.LBB0_1959:
	s_waitcnt vmcnt(0) lgkmcnt(0)
	v_readlane_b32 s0, v242, 42
	v_readlane_b32 s1, v242, 43
	v_readlane_b32 s4, v242, 3
	v_readlane_b32 s5, v242, 4
	s_lshr_b32 s6, s24, 2
	s_and_b32 s7, s24, 3
	s_cmp_gt_u32 s6, 11
	s_cselect_b32 s8, 1, 0
	s_mul_i32 s9, s8, 12
	s_sub_i32 s9, s6, s9
	s_sub_u32 s0, s0, 0x118
	s_subb_u32 s1, s1, 0
	s_load_dwordx2 s[2:3], s[0:1], 0x30
	s_lshr_b32 s10, s9, 1
	s_and_b32 s11, s9, 1
	s_lshl_b32 s29, s8, 1
	s_add_i32 s29, s29, 1
	s_lshl_b32 s29, s29, 1
	s_add_i32 s29, s29, s11
	s_mul_i32 s29, s29, 6
	s_add_i32 s29, s29, s10
	s_lshl_b32 s29, s29, 14
	v_and_b32_e32 v20, 15, v137
	v_lshrrev_b32_e32 v21, 4, v137
	v_lshlrev_b32_e32 v22, 4, v137
	s_lshl_b32 s38, s7, 12
	v_add_u32_e32 v22, s38, v22
	s_waitcnt lgkmcnt(0)
	s_add_u32 s2, s2, s29
	s_addc_u32 s3, s3, 0
	global_load_dwordx4 v[0:3], v22, s[2:3]
	s_mul_i32 s38, s11, 0xf00000
	s_mul_i32 s39, s11, 0x780000
	s_add_u32 s29, s38, 0x9278100
	s_add_u32 s12, s4, s29
	s_addc_u32 s13, s5, 0
	s_add_u32 s29, s39, 0xb078100
	s_add_u32 s14, s4, s29
	s_addc_u32 s15, s5, 0
	s_add_u32 s29, s39, 0xbf78100
	s_add_u32 s18, s4, s29
	s_addc_u32 s19, s5, 0
	s_add_u32 s29, s39, 0xddc8100
	s_add_u32 s22, s4, s29
	s_addc_u32 s23, s5, 0
	s_add_u32 s16, s4, 0xce78100
	s_addc_u32 s17, s5, 0
	s_add_u32 s20, s4, 0x5b78100
	s_addc_u32 s21, s5, 0
	s_lshl_b32 s38, s11, 1
	s_sub_i32 s38, 1, s38
	s_mul_i32 s25, s38, 24576
	s_mul_i32 s26, s38, 12288
	s_mul_i32 s27, s38, 0x16000
	s_lshl_b32 s39, s8, 10
	s_addk_i32 s39, 0x2000
	s_mul_i32 s44, s11, 1023
	s_add_i32 s39, s39, s44
	v_mul_i32_i24_e32 v23, s38, v21
	v_mul_i32_i24_e32 v24, s38, v20
	v_add_u32_e32 v23, s39, v23
	v_add_u32_e32 v24, s39, v24
	s_lshl_b32 s38, s10, 8
	s_lshl_b32 s39, s10, 7
	s_movk_i32 s44, 0x600
	v_lshlrev_b32_e32 v25, 4, v20
	v_mul_lo_u32 v174, v23, s44
	v_add3_u32 v174, v174, s38, v25
	s_movk_i32 s44, 0x300
	v_lshlrev_b32_e32 v26, 3, v20
	v_mul_lo_u32 v175, v23, s44
	v_add3_u32 v175, v175, s39, v26
	v_mul_lo_u32 v145, v24, s44
	s_lshl_b32 s44, s7, 5
	s_add_i32 s44, s44, s39
	v_lshlrev_b32_e32 v27, 1, v21
	v_add3_u32 v145, v145, s44, v27
	s_movk_i32 s44, 0x1600
	v_mul_lo_u32 v180, v23, s44
	v_lshlrev_b32_e32 v28, 2, v20
	s_lshl_b32 s44, s7, 6
	s_add_i32 s44, s44, s38
	s_addk_i32 s44, 0xc00
	v_add3_u32 v181, v180, s44, v28
	v_add3_u32 v180, v180, s38, v25
	v_mov_b32_e32 v88, v25
	v_lshlrev_b32_e32 v90, 4, v21
	v_mul_u32_u24_e32 v91, 0x600, v21
	v_add_u32_e32 v91, v91, v25
	v_and_b32_e32 v29, 1, v20
	v_and_b32_e32 v30, 2, v20
	v_cmp_ne_u32_e64 s[30:31], 0, v29
	v_cmp_ne_u32_e64 s[34:35], 0, v30
	v_and_b32_e32 v29, 3, v20
	v_cmp_eq_u32_e64 s[36:37], 3, v29
	s_mov_b32 s28, 0
	s_setprio 3
	global_load_dwordx4 v[104:107], v174, s[12:13]
	global_load_dwordx2 v[146:147], v175, s[14:15]
	global_load_dwordx2 v[148:149], v175, s[16:17]
	global_load_dwordx2 v[150:151], v175, s[18:19]
	global_load_dwordx4 v[108:111], v180, s[20:21]
	global_load_dword v170, v181, s[20:21]
	v_add_u32_e32 v174, s25, v174
	v_add_u32_e32 v175, s26, v175
	v_add_u32_e32 v180, s27, v180
	v_add_u32_e32 v181, s27, v181
	global_load_dwordx4 v[112:115], v174, s[12:13]
	global_load_dwordx2 v[152:153], v175, s[14:15]
	global_load_dwordx2 v[154:155], v175, s[16:17]
	global_load_dwordx2 v[156:157], v175, s[18:19]
	global_load_dwordx4 v[116:119], v180, s[20:21]
	global_load_dword v171, v181, s[20:21]
	v_add_u32_e32 v174, s25, v174
	v_add_u32_e32 v175, s26, v175
	v_add_u32_e32 v180, s27, v180
	v_add_u32_e32 v181, s27, v181
	global_load_dwordx4 v[120:123], v174, s[12:13]
	global_load_dwordx2 v[158:159], v175, s[14:15]
	global_load_dwordx2 v[160:161], v175, s[16:17]
	global_load_dwordx2 v[162:163], v175, s[18:19]
	global_load_dwordx4 v[124:127], v180, s[20:21]
	global_load_dword v172, v181, s[20:21]
	v_add_u32_e32 v174, s25, v174
	v_add_u32_e32 v175, s26, v175
	v_add_u32_e32 v180, s27, v180
	v_add_u32_e32 v181, s27, v181
	global_load_dwordx4 v[128:131], v174, s[12:13]
	global_load_dwordx2 v[164:165], v175, s[14:15]
	global_load_dwordx2 v[166:167], v175, s[16:17]
	global_load_dwordx2 v[168:169], v175, s[18:19]
	global_load_dwordx4 v[132:135], v180, s[20:21]
	global_load_dword v173, v181, s[20:21]
	v_add_u32_e32 v174, s25, v174
	v_add_u32_e32 v175, s26, v175
	v_add_u32_e32 v180, s27, v180
	v_add_u32_e32 v181, s27, v181
	s_waitcnt vmcnt(18)
	ds_write_b128 v91, v[104:107] offset:0
	ds_write_b128 v91, v[108:111] offset:1024
	ds_write_b32 v91, v170 offset:1280
	v_lshlrev_b32_e32 v176, 16, v146
	v_and_b32_e32 v177, 0xffff0000, v146
	v_lshlrev_b32_e32 v178, 16, v147
	v_and_b32_e32 v179, 0xffff0000, v147
	ds_write_b128 v91, v[176:179] offset:256
	v_lshlrev_b32_e32 v176, 16, v148
	v_and_b32_e32 v177, 0xffff0000, v148
	v_lshlrev_b32_e32 v178, 16, v149
	v_and_b32_e32 v179, 0xffff0000, v149
	ds_write_b128 v91, v[176:179] offset:512
	v_lshlrev_b32_e32 v176, 16, v150
	v_and_b32_e32 v177, 0xffff0000, v150
	v_lshlrev_b32_e32 v178, 16, v151
	v_and_b32_e32 v179, 0xffff0000, v151
	ds_write_b128 v91, v[176:179] offset:768
	s_waitcnt lgkmcnt(0)
	s_barrier
	ds_read_b128 v[28:31], v88 offset:512
	ds_read_b128 v[24:27], v88 offset:256
	ds_read_b128 v[20:23], v88 offset:0
	ds_read_b128 v[32:35], v88 offset:768
	ds_read_b128 v[36:39], v88 offset:1024
	ds_read2st64_b32 v[16:17], v90 offset0:5 offset1:11
	ds_read_b128 v[48:51], v88 offset:2048
	ds_read_b128 v[44:47], v88 offset:1792
	ds_read_b128 v[40:43], v88 offset:1536
	ds_read_b128 v[52:55], v88 offset:2304
	ds_read_b128 v[56:59], v88 offset:2560
